# back-edge rotation: K-loop counter/pointer SALU block moved in front of the segment-closing s_barrier in P1/P6/P7/P8 loops (on top of tile-edge version)
# baseline (speedup 1.0000x reference)
; #define PG8_STAGE(bufoff, gbase, voff) do { _Pragma("unroll") for (int _i = 0; _i < 2; ++_i) \
;         __builtin_amdgcn_global_load_lds((const unsigned*)((const char*)(gbase) + (voff)[_i]), (LAS unsigned*)(lds + (bufoff) + ldsw + _i * 8192), 16, 0, 0); } while (0)
; #define PG8_LDA(dst, b, h) do { _Pragma("unroll") for (int m = 0; m < 4; ++m) _Pragma("unroll") for (int k = 0; k < 2; ++k) dst[m][k] = *(const LAS bf16x8*)(lds + PG8_SA(b, h) + aoff + m * 2048 + k * 1024); } while (0)
; #define PG8_LDB(dst, b, h) do { _Pragma("unroll") for (int n = 0; n < 2; ++n) _Pragma("unroll") for (int k = 0; k < 2; ++k) dst[n][k] = *(const LAS bf16x8*)(lds + PG8_SB(b, h) + boff + n * 2048 + k * 1024); } while (0)
; #define PG8_MMA(ai, bj, At, Bt) do { __builtin_amdgcn_s_setprio(1); _Pragma("unroll") for (int m = 0; m < 4; ++m) _Pragma("unroll") for (int n = 0; n < 2; ++n) _Pragma("unroll") for (int k = 0; k < 2; ++k) \
;         acc[ai][bj][m][n] = __builtin_amdgcn_mfma_f32_16x16x32_bf16(Bt[n][k], At[m][k], acc[ai][bj][m][n], 0, 0, 0); __builtin_amdgcn_s_setprio(0); } while (0)
; #define PG8_WAIT_V(n) asm volatile("s_waitcnt vmcnt(" #n ")" ::: "memory")
; #define PG8_WAIT_L(n) asm volatile("s_waitcnt lgkmcnt(" #n ")" ::: "memory")
; #define PG8_BAR __builtin_amdgcn_s_barrier()
; #define PG8_SCHED __builtin_amdgcn_sched_barrier(0)
; template <class Epi, class Sched>
; __device__ __forceinline__ void gemm_phase(LAS unsigned char* lds, const Gemm g, const Sched& S, const Epi& E) {
;     ...
;         for (int t = 0; t < nt; t += 2) {
;             const bool last = (t == nt - 2);
;             const char* a1 = cA + (size_t)(t + 1) * kstep;
;             const char* a2 = last ? nA : cA + (size_t)(t + 2) * kstep; const char* b2 = last ? nB : cB + (size_t)(t + 2) * kstep;
;             const char* a3 = a2 + kstep; const char* b3 = b2 + kstep;
;             PG8_LDB(B0, 0, 0); PG8_LDB(B1, 0, 1); PG8_SCHED; PG8_LDA(At, 0, 0); PG8_STAGE(PG8_SA(1, 1), a1 + hstepA, voffA);
;             PG8_WAIT_V(8); PG8_WAIT_L(0); PG8_BAR; PG8_MMA(0, 0, At, B0); PG8_MMA(0, 1, At, B1); PG8_BAR; PG8_SCHED;
;             PG8_LDA(At, 0, 1); PG8_STAGE(PG8_SB(0, 0), b2, voffB); PG8_STAGE(PG8_SB(0, 1), b2 + hstepB, voffB); PG8_STAGE(PG8_SA(0, 0), a2, voffA);
.Ledge_p1:
.LBB0_148:
	ds_read_b128 v[154:157], v167
	ds_read_b128 v[158:161], v167 offset:1024
	ds_read_b128 v[170:173], v167 offset:2048
	ds_read_b128 v[174:177], v167 offset:3072
	ds_read_b128 v[178:181], v168
	ds_read_b128 v[182:185], v168 offset:1024
	ds_read_b128 v[186:189], v168 offset:2048
	ds_read_b128 v[190:193], v168 offset:3072
	s_add_u32 s48, vcc_lo, 0xfff80080
	s_addc_u32 s49, vcc_hi, -1
	s_cmp_eq_u32 s93, 28
	s_cselect_b32 s97, s2, s49
	s_cselect_b32 s96, s7, s48
	s_cselect_b32 s71, s9, s75
	s_cselect_b32 s70, s34, s35
	v_lshl_add_u64 v[162:163], vcc, 0, v[144:145]
	s_add_i32 m0, s88, 0xc000
	ds_read_b128 v[194:197], v169
	ds_read_b128 v[198:201], v169 offset:1024
	ds_read_b128 v[202:205], v169 offset:2048
	ds_read_b128 v[206:209], v169 offset:3072
	ds_read_b128 v[210:213], v169 offset:4096
	ds_read_b128 v[214:217], v169 offset:5120
	ds_read_b128 v[218:221], v169 offset:6144
	ds_read_b128 v[222:225], v169 offset:7168
	global_load_lds_dwordx4 v[162:163], off
	v_lshl_add_u64 v[162:163], vcc, 0, v[146:147]
	s_add_i32 m0, s88, 0xe000
	s_nop 0
	global_load_lds_dwordx4 v[162:163], off
	s_waitcnt vmcnt(8)
	s_waitcnt lgkmcnt(0)
	s_barrier
	s_setprio 1
	s_waitcnt lgkmcnt(0)
	v_mfma_f32_16x16x32_bf16 v[124:127], v[154:157], v[194:197], v[124:127]
	v_mfma_f32_16x16x32_bf16 v[120:123], v[170:173], v[194:197], v[120:123]
	v_mfma_f32_16x16x32_bf16 v[108:111], v[154:157], v[202:205], v[108:111]
	v_mfma_f32_16x16x32_bf16 v[104:107], v[170:173], v[202:205], v[104:107]
	v_mfma_f32_16x16x32_bf16 v[92:95], v[154:157], v[210:213], v[92:95]
	v_mfma_f32_16x16x32_bf16 v[88:91], v[170:173], v[210:213], v[88:91]
	v_mfma_f32_16x16x32_bf16 v[76:79], v[154:157], v[218:221], v[76:79]
	v_mfma_f32_16x16x32_bf16 v[72:75], v[170:173], v[218:221], v[72:75]
	v_mfma_f32_16x16x32_bf16 v[124:127], v[158:161], v[198:201], v[124:127]
	v_mfma_f32_16x16x32_bf16 v[120:123], v[174:177], v[198:201], v[120:123]
	v_mfma_f32_16x16x32_bf16 v[108:111], v[158:161], v[206:209], v[108:111]
	v_mfma_f32_16x16x32_bf16 v[104:107], v[174:177], v[206:209], v[104:107]
	v_mfma_f32_16x16x32_bf16 v[92:95], v[158:161], v[214:217], v[92:95]
	v_mfma_f32_16x16x32_bf16 v[88:91], v[174:177], v[214:217], v[88:91]
	v_mfma_f32_16x16x32_bf16 v[76:79], v[158:161], v[222:225], v[76:79]
	v_mfma_f32_16x16x32_bf16 v[72:75], v[174:177], v[222:225], v[72:75]
	s_setprio 0
	s_setprio 1
	v_mfma_f32_16x16x32_bf16 v[116:119], v[178:181], v[194:197], v[116:119]
	v_mfma_f32_16x16x32_bf16 v[112:115], v[186:189], v[194:197], v[112:115]
	v_mfma_f32_16x16x32_bf16 v[100:103], v[178:181], v[202:205], v[100:103]
	v_mfma_f32_16x16x32_bf16 v[96:99], v[186:189], v[202:205], v[96:99]
	v_mfma_f32_16x16x32_bf16 v[84:87], v[178:181], v[210:213], v[84:87]
	v_mfma_f32_16x16x32_bf16 v[80:83], v[186:189], v[210:213], v[80:83]
	v_mfma_f32_16x16x32_bf16 v[68:71], v[178:181], v[218:221], v[68:71]
	v_mfma_f32_16x16x32_bf16 v[64:67], v[186:189], v[218:221], v[64:67]
	v_mfma_f32_16x16x32_bf16 v[116:119], v[182:185], v[198:201], v[116:119]
	v_mfma_f32_16x16x32_bf16 v[112:115], v[190:193], v[198:201], v[112:115]
	v_mfma_f32_16x16x32_bf16 v[100:103], v[182:185], v[206:209], v[100:103]
	v_mfma_f32_16x16x32_bf16 v[96:99], v[190:193], v[206:209], v[96:99]
	v_mfma_f32_16x16x32_bf16 v[84:87], v[182:185], v[214:217], v[84:87]
	v_mfma_f32_16x16x32_bf16 v[80:83], v[190:193], v[214:217], v[80:83]
	v_mfma_f32_16x16x32_bf16 v[68:71], v[182:185], v[222:225], v[68:71]
	v_mfma_f32_16x16x32_bf16 v[64:67], v[190:193], v[222:225], v[64:67]
	s_setprio 0
	s_barrier
	s_add_i32 s48, s62, s33
	v_lshl_add_u64 v[162:163], s[70:71], 0, v[130:131]
	s_mov_b32 m0, s48
	ds_read_b128 v[194:197], v169 offset:16384
	ds_read_b128 v[198:201], v169 offset:17408
	ds_read_b128 v[202:205], v169 offset:18432
	ds_read_b128 v[206:209], v169 offset:19456
	ds_read_b128 v[210:213], v169 offset:20480
	ds_read_b128 v[214:217], v169 offset:21504
	ds_read_b128 v[218:221], v169 offset:22528
	ds_read_b128 v[222:225], v169 offset:23552
	global_load_lds_dwordx4 v[162:163], off
	s_add_i32 m0, s48, 0x2000
	s_add_u32 s48, s70, 0x80000
	v_lshl_add_u64 v[226:227], s[70:71], 0, v[134:135]
	s_addc_u32 s49, s71, 0
	s_add_i32 s95, s63, s33
	global_load_lds_dwordx4 v[226:227], off
	v_lshl_add_u64 v[228:229], s[48:49], 0, v[130:131]
	s_mov_b32 m0, s95
	v_lshl_add_u64 v[230:231], s[96:97], 0, v[132:133]
	global_load_lds_dwordx4 v[228:229], off
	v_lshl_add_u64 v[228:229], s[48:49], 0, v[134:135]
	s_add_i32 m0, s95, 0x2000
	s_nop 0
	global_load_lds_dwordx4 v[228:229], off
	v_lshl_add_u64 v[228:229], s[96:97], 0, v[128:129]
	s_mov_b32 m0, s88
	s_nop 0
	global_load_lds_dwordx4 v[228:229], off
	s_mov_b32 m0, s89
	s_nop 0
	global_load_lds_dwordx4 v[230:231], off
	s_waitcnt vmcnt(8)
	s_waitcnt lgkmcnt(0)
	s_barrier
; #define PG8_STAGE(bufoff, gbase, voff) do { _Pragma("unroll") for (int _i = 0; _i < 2; ++_i) \
;         __builtin_amdgcn_global_load_lds((const unsigned*)((const char*)(gbase) + (voff)[_i]), (LAS unsigned*)(lds + (bufoff) + ldsw + _i * 8192), 16, 0, 0); } while (0)
; #define PG8_LDA(dst, b, h) do { _Pragma("unroll") for (int m = 0; m < 4; ++m) _Pragma("unroll") for (int k = 0; k < 2; ++k) dst[m][k] = *(const LAS bf16x8*)(lds + PG8_SA(b, h) + aoff + m * 2048 + k * 1024); } while (0)
; #define PG8_LDB(dst, b, h) do { _Pragma("unroll") for (int n = 0; n < 2; ++n) _Pragma("unroll") for (int k = 0; k < 2; ++k) dst[n][k] = *(const LAS bf16x8*)(lds + PG8_SB(b, h) + boff + n * 2048 + k * 1024); } while (0)
; #define PG8_MMA(ai, bj, At, Bt) do { __builtin_amdgcn_s_setprio(1); _Pragma("unroll") for (int m = 0; m < 4; ++m) _Pragma("unroll") for (int n = 0; n < 2; ++n) _Pragma("unroll") for (int k = 0; k < 2; ++k) \
;         acc[ai][bj][m][n] = __builtin_amdgcn_mfma_f32_16x16x32_bf16(Bt[n][k], At[m][k], acc[ai][bj][m][n], 0, 0, 0); __builtin_amdgcn_s_setprio(0); } while (0)
; #define PG8_WAIT_V(n) asm volatile("s_waitcnt vmcnt(" #n ")" ::: "memory")
; #define PG8_WAIT_L(n) asm volatile("s_waitcnt lgkmcnt(" #n ")" ::: "memory")
; #define PG8_BAR __builtin_amdgcn_s_barrier()
; #define PG8_SCHED __builtin_amdgcn_sched_barrier(0)
; template <class Epi, class Sched>
; __device__ __forceinline__ void gemm_phase(LAS unsigned char* lds, const Gemm g, const Sched& S, const Epi& E) {
;     ...
;             PG8_WAIT_V(8); PG8_WAIT_L(0); PG8_BAR; PG8_MMA(1, 0, At, B0); PG8_MMA(1, 1, At, B1); PG8_BAR; PG8_SCHED;
;             PG8_LDB(B0, 1, 0); PG8_LDB(B1, 1, 1); PG8_SCHED; PG8_LDA(At, 1, 0); PG8_STAGE(PG8_SA(0, 1), a2 + hstepA, voffA);
;             PG8_WAIT_V(8); PG8_WAIT_L(0); PG8_BAR; PG8_MMA(0, 0, At, B0); PG8_MMA(0, 1, At, B1); PG8_BAR; PG8_SCHED;
	s_setprio 1
	s_waitcnt lgkmcnt(0)
	v_mfma_f32_16x16x32_bf16 v[60:63], v[154:157], v[194:197], v[60:63]
	v_mfma_f32_16x16x32_bf16 v[56:59], v[170:173], v[194:197], v[56:59]
	v_mfma_f32_16x16x32_bf16 v[44:47], v[154:157], v[202:205], v[44:47]
	v_mfma_f32_16x16x32_bf16 v[40:43], v[170:173], v[202:205], v[40:43]
	v_mfma_f32_16x16x32_bf16 v[28:31], v[154:157], v[210:213], v[28:31]
	v_mfma_f32_16x16x32_bf16 v[24:27], v[170:173], v[210:213], v[24:27]
	v_mfma_f32_16x16x32_bf16 v[12:15], v[154:157], v[218:221], v[12:15]
	v_mfma_f32_16x16x32_bf16 v[8:11], v[170:173], v[218:221], v[8:11]
	v_mfma_f32_16x16x32_bf16 v[60:63], v[158:161], v[198:201], v[60:63]
	v_mfma_f32_16x16x32_bf16 v[56:59], v[174:177], v[198:201], v[56:59]
	v_mfma_f32_16x16x32_bf16 v[44:47], v[158:161], v[206:209], v[44:47]
	v_mfma_f32_16x16x32_bf16 v[40:43], v[174:177], v[206:209], v[40:43]
	v_mfma_f32_16x16x32_bf16 v[28:31], v[158:161], v[214:217], v[28:31]
	v_mfma_f32_16x16x32_bf16 v[24:27], v[174:177], v[214:217], v[24:27]
	v_mfma_f32_16x16x32_bf16 v[12:15], v[158:161], v[222:225], v[12:15]
	v_mfma_f32_16x16x32_bf16 v[8:11], v[174:177], v[222:225], v[8:11]
	s_setprio 0
	s_setprio 1
	v_mfma_f32_16x16x32_bf16 v[52:55], v[178:181], v[194:197], v[52:55]
	v_mfma_f32_16x16x32_bf16 v[48:51], v[186:189], v[194:197], v[48:51]
	v_mfma_f32_16x16x32_bf16 v[36:39], v[178:181], v[202:205], v[36:39]
	v_mfma_f32_16x16x32_bf16 v[32:35], v[186:189], v[202:205], v[32:35]
	v_mfma_f32_16x16x32_bf16 v[20:23], v[178:181], v[210:213], v[20:23]
	v_mfma_f32_16x16x32_bf16 v[16:19], v[186:189], v[210:213], v[16:19]
	v_mfma_f32_16x16x32_bf16 v[4:7], v[178:181], v[218:221], v[4:7]
	v_mfma_f32_16x16x32_bf16 v[0:3], v[186:189], v[218:221], v[0:3]
	v_mfma_f32_16x16x32_bf16 v[52:55], v[182:185], v[198:201], v[52:55]
	v_mfma_f32_16x16x32_bf16 v[48:51], v[190:193], v[198:201], v[48:51]
	v_mfma_f32_16x16x32_bf16 v[36:39], v[182:185], v[206:209], v[36:39]
	v_mfma_f32_16x16x32_bf16 v[32:35], v[190:193], v[206:209], v[32:35]
	v_mfma_f32_16x16x32_bf16 v[20:23], v[182:185], v[214:217], v[20:23]
	v_mfma_f32_16x16x32_bf16 v[16:19], v[190:193], v[214:217], v[16:19]
	v_mfma_f32_16x16x32_bf16 v[4:7], v[182:185], v[222:225], v[4:7]
	v_mfma_f32_16x16x32_bf16 v[0:3], v[190:193], v[222:225], v[0:3]
	s_setprio 0
	s_barrier
	s_add_i32 s95, 0, 0x18000
	v_add_u32_e32 v138, s95, v141
	s_add_i32 s78, 0, 0x1c000
	ds_read_b128 v[154:157], v138
	ds_read_b128 v[158:161], v138 offset:1024
	ds_read_b128 v[170:173], v138 offset:2048
	ds_read_b128 v[174:177], v138 offset:3072
	v_add_u32_e32 v138, s78, v141
	ds_read_b128 v[178:181], v138
	ds_read_b128 v[182:185], v138 offset:1024
	ds_read_b128 v[186:189], v138 offset:2048
	ds_read_b128 v[190:193], v138 offset:3072
	s_add_u32 s48, s96, 0x80000
	s_addc_u32 s49, s97, 0
	s_mov_b32 m0, s60
	v_lshl_add_u64 v[232:233], s[48:49], 0, v[128:129]
	ds_read_b128 v[194:197], v169 offset:32768
	ds_read_b128 v[198:201], v169 offset:33792
	ds_read_b128 v[202:205], v169 offset:34816
	ds_read_b128 v[206:209], v169 offset:35840
	ds_read_b128 v[210:213], v169 offset:36864
	ds_read_b128 v[214:217], v169 offset:37888
	ds_read_b128 v[218:221], v169 offset:38912
	ds_read_b128 v[222:225], v169 offset:39936
	global_load_lds_dwordx4 v[232:233], off
	v_lshl_add_u64 v[232:233], s[48:49], 0, v[132:133]
	s_mov_b32 m0, s61
	s_nop 0
	global_load_lds_dwordx4 v[232:233], off
	s_waitcnt vmcnt(8)
	s_waitcnt lgkmcnt(0)
	s_barrier
	s_setprio 1
	s_waitcnt lgkmcnt(0)
	v_mfma_f32_16x16x32_bf16 v[124:127], v[154:157], v[194:197], v[124:127]
	v_mfma_f32_16x16x32_bf16 v[120:123], v[170:173], v[194:197], v[120:123]
	v_mfma_f32_16x16x32_bf16 v[108:111], v[154:157], v[202:205], v[108:111]
	v_mfma_f32_16x16x32_bf16 v[104:107], v[170:173], v[202:205], v[104:107]
	v_mfma_f32_16x16x32_bf16 v[92:95], v[154:157], v[210:213], v[92:95]
	v_mfma_f32_16x16x32_bf16 v[88:91], v[170:173], v[210:213], v[88:91]
	v_mfma_f32_16x16x32_bf16 v[76:79], v[154:157], v[218:221], v[76:79]
	v_mfma_f32_16x16x32_bf16 v[72:75], v[170:173], v[218:221], v[72:75]
	v_mfma_f32_16x16x32_bf16 v[124:127], v[158:161], v[198:201], v[124:127]
	v_mfma_f32_16x16x32_bf16 v[120:123], v[174:177], v[198:201], v[120:123]
	v_mfma_f32_16x16x32_bf16 v[108:111], v[158:161], v[206:209], v[108:111]
	v_mfma_f32_16x16x32_bf16 v[104:107], v[174:177], v[206:209], v[104:107]
	v_mfma_f32_16x16x32_bf16 v[92:95], v[158:161], v[214:217], v[92:95]
	v_mfma_f32_16x16x32_bf16 v[88:91], v[174:177], v[214:217], v[88:91]
	v_mfma_f32_16x16x32_bf16 v[76:79], v[158:161], v[222:225], v[76:79]
	v_mfma_f32_16x16x32_bf16 v[72:75], v[174:177], v[222:225], v[72:75]
	s_setprio 0
	s_setprio 1
	v_mfma_f32_16x16x32_bf16 v[116:119], v[178:181], v[194:197], v[116:119]
	v_mfma_f32_16x16x32_bf16 v[112:115], v[186:189], v[194:197], v[112:115]
	v_mfma_f32_16x16x32_bf16 v[100:103], v[178:181], v[202:205], v[100:103]
	v_mfma_f32_16x16x32_bf16 v[96:99], v[186:189], v[202:205], v[96:99]
	v_mfma_f32_16x16x32_bf16 v[84:87], v[178:181], v[210:213], v[84:87]
	v_mfma_f32_16x16x32_bf16 v[80:83], v[186:189], v[210:213], v[80:83]
	v_mfma_f32_16x16x32_bf16 v[68:71], v[178:181], v[218:221], v[68:71]
	v_mfma_f32_16x16x32_bf16 v[64:67], v[186:189], v[218:221], v[64:67]
	v_mfma_f32_16x16x32_bf16 v[116:119], v[182:185], v[198:201], v[116:119]
	v_mfma_f32_16x16x32_bf16 v[112:115], v[190:193], v[198:201], v[112:115]
	v_mfma_f32_16x16x32_bf16 v[100:103], v[182:185], v[206:209], v[100:103]
	v_mfma_f32_16x16x32_bf16 v[96:99], v[190:193], v[206:209], v[96:99]
	v_mfma_f32_16x16x32_bf16 v[84:87], v[182:185], v[214:217], v[84:87]
	v_mfma_f32_16x16x32_bf16 v[80:83], v[190:193], v[214:217], v[80:83]
	v_mfma_f32_16x16x32_bf16 v[68:71], v[182:185], v[222:225], v[68:71]
	v_mfma_f32_16x16x32_bf16 v[64:67], v[190:193], v[222:225], v[64:67]
	s_setprio 0
	s_barrier
; #define PG8_STAGE(bufoff, gbase, voff) do { _Pragma("unroll") for (int _i = 0; _i < 2; ++_i) \
;         __builtin_amdgcn_global_load_lds((const unsigned*)((const char*)(gbase) + (voff)[_i]), (LAS unsigned*)(lds + (bufoff) + ldsw + _i * 8192), 16, 0, 0); } while (0)
; #define PG8_LDA(dst, b, h) do { _Pragma("unroll") for (int m = 0; m < 4; ++m) _Pragma("unroll") for (int k = 0; k < 2; ++k) dst[m][k] = *(const LAS bf16x8*)(lds + PG8_SA(b, h) + aoff + m * 2048 + k * 1024); } while (0)
; #define PG8_MMA(ai, bj, At, Bt) do { __builtin_amdgcn_s_setprio(1); _Pragma("unroll") for (int m = 0; m < 4; ++m) _Pragma("unroll") for (int n = 0; n < 2; ++n) _Pragma("unroll") for (int k = 0; k < 2; ++k) \
;         acc[ai][bj][m][n] = __builtin_amdgcn_mfma_f32_16x16x32_bf16(Bt[n][k], At[m][k], acc[ai][bj][m][n], 0, 0, 0); __builtin_amdgcn_s_setprio(0); } while (0)
; #define PG8_WAIT_V(n) asm volatile("s_waitcnt vmcnt(" #n ")" ::: "memory")
; #define PG8_WAIT_L(n) asm volatile("s_waitcnt lgkmcnt(" #n ")" ::: "memory")
; #define PG8_BAR __builtin_amdgcn_s_barrier()
; #define PG8_SCHED __builtin_amdgcn_sched_barrier(0)
; template <class Epi, class Sched>
; __device__ __forceinline__ void gemm_phase(LAS unsigned char* lds, const Gemm g, const Sched& S, const Epi& E) {
;     ...
;             PG8_LDA(At, 1, 1); PG8_STAGE(PG8_SB(1, 0), b3, voffB); PG8_STAGE(PG8_SB(1, 1), b3 + hstepB, voffB); PG8_STAGE(PG8_SA(1, 0), a3, voffA);
;             PG8_WAIT_V(8); PG8_WAIT_L(0); PG8_BAR; PG8_MMA(1, 0, At, B0); PG8_MMA(1, 1, At, B1); PG8_BAR; PG8_SCHED;
;         }
	s_add_i32 s48, s95, s33
	v_lshl_add_u64 v[162:163], v[162:163], 0, s[84:85]
	s_mov_b32 m0, s48
	ds_read_b128 v[194:197], v169 offset:49152
	ds_read_b128 v[198:201], v169 offset:50176
	ds_read_b128 v[202:205], v169 offset:51200
	ds_read_b128 v[206:209], v169 offset:52224
	ds_read_b128 v[210:213], v169 offset:53248
	ds_read_b128 v[214:217], v169 offset:54272
	ds_read_b128 v[218:221], v169 offset:55296
	ds_read_b128 v[222:225], v169 offset:56320
	global_load_lds_dwordx4 v[162:163], off
	s_add_i32 m0, s48, 0x2000
	s_add_u32 s48, s70, 0x80080
	v_lshl_add_u64 v[162:163], v[226:227], 0, s[84:85]
	s_addc_u32 s49, s71, 0
	s_add_i32 s70, s78, s33
	global_load_lds_dwordx4 v[162:163], off
	v_lshl_add_u64 v[162:163], s[48:49], 0, v[130:131]
	s_mov_b32 m0, s70
	s_nop 0
	global_load_lds_dwordx4 v[162:163], off
	v_lshl_add_u64 v[162:163], s[48:49], 0, v[134:135]
	s_add_i32 m0, s70, 0x2000
	s_nop 0
	global_load_lds_dwordx4 v[162:163], off
	v_lshl_add_u64 v[162:163], v[228:229], 0, s[84:85]
	s_mov_b32 m0, s90
	s_nop 0
	global_load_lds_dwordx4 v[162:163], off
	v_lshl_add_u64 v[162:163], v[230:231], 0, s[84:85]
	s_mov_b32 m0, s91
	s_nop 0
	global_load_lds_dwordx4 v[162:163], off
	s_waitcnt vmcnt(8)
	s_waitcnt lgkmcnt(0)
	s_barrier
	s_setprio 1
	s_waitcnt lgkmcnt(0)
	v_mfma_f32_16x16x32_bf16 v[60:63], v[154:157], v[194:197], v[60:63]
	v_mfma_f32_16x16x32_bf16 v[56:59], v[170:173], v[194:197], v[56:59]
	v_mfma_f32_16x16x32_bf16 v[44:47], v[154:157], v[202:205], v[44:47]
	v_mfma_f32_16x16x32_bf16 v[40:43], v[170:173], v[202:205], v[40:43]
	v_mfma_f32_16x16x32_bf16 v[28:31], v[154:157], v[210:213], v[28:31]
	v_mfma_f32_16x16x32_bf16 v[24:27], v[170:173], v[210:213], v[24:27]
	v_mfma_f32_16x16x32_bf16 v[12:15], v[154:157], v[218:221], v[12:15]
	v_mfma_f32_16x16x32_bf16 v[8:11], v[170:173], v[218:221], v[8:11]
	v_mfma_f32_16x16x32_bf16 v[60:63], v[158:161], v[198:201], v[60:63]
	v_mfma_f32_16x16x32_bf16 v[56:59], v[174:177], v[198:201], v[56:59]
	v_mfma_f32_16x16x32_bf16 v[44:47], v[158:161], v[206:209], v[44:47]
	v_mfma_f32_16x16x32_bf16 v[40:43], v[174:177], v[206:209], v[40:43]
	v_mfma_f32_16x16x32_bf16 v[28:31], v[158:161], v[214:217], v[28:31]
	v_mfma_f32_16x16x32_bf16 v[24:27], v[174:177], v[214:217], v[24:27]
	v_mfma_f32_16x16x32_bf16 v[12:15], v[158:161], v[222:225], v[12:15]
	v_mfma_f32_16x16x32_bf16 v[8:11], v[174:177], v[222:225], v[8:11]
	s_setprio 0
	s_setprio 1
	v_mfma_f32_16x16x32_bf16 v[52:55], v[178:181], v[194:197], v[52:55]
	v_mfma_f32_16x16x32_bf16 v[48:51], v[186:189], v[194:197], v[48:51]
	v_mfma_f32_16x16x32_bf16 v[36:39], v[178:181], v[202:205], v[36:39]
	v_mfma_f32_16x16x32_bf16 v[32:35], v[186:189], v[202:205], v[32:35]
	v_mfma_f32_16x16x32_bf16 v[20:23], v[178:181], v[210:213], v[20:23]
	v_mfma_f32_16x16x32_bf16 v[16:19], v[186:189], v[210:213], v[16:19]
	v_mfma_f32_16x16x32_bf16 v[4:7], v[178:181], v[218:221], v[4:7]
	v_mfma_f32_16x16x32_bf16 v[0:3], v[186:189], v[218:221], v[0:3]
	v_mfma_f32_16x16x32_bf16 v[52:55], v[182:185], v[198:201], v[52:55]
	v_mfma_f32_16x16x32_bf16 v[48:51], v[190:193], v[198:201], v[48:51]
	v_mfma_f32_16x16x32_bf16 v[36:39], v[182:185], v[206:209], v[36:39]
	v_mfma_f32_16x16x32_bf16 v[32:35], v[190:193], v[206:209], v[32:35]
	v_mfma_f32_16x16x32_bf16 v[20:23], v[182:185], v[214:217], v[20:23]
	v_mfma_f32_16x16x32_bf16 v[16:19], v[190:193], v[214:217], v[16:19]
	v_mfma_f32_16x16x32_bf16 v[4:7], v[182:185], v[222:225], v[4:7]
	v_mfma_f32_16x16x32_bf16 v[0:3], v[190:193], v[222:225], v[0:3]
	s_setprio 0
	s_add_i32 s93, s93, 2
	s_add_u32 vcc_lo, vcc_lo, 0x100
	s_addc_u32 vcc_hi, vcc_hi, 0
	s_add_u32 s35, s35, 0x100
	s_addc_u32 s75, s75, 0
	s_cmp_gt_u32 s93, 29
	s_barrier
	s_cbranch_scc0 .LBB0_148
	s_and_b64 vcc, exec, s[86:87]
	s_cbranch_vccz .LBB0_151
	s_barrier

; #define PG8_STAGE(bufoff, gbase, voff) do { _Pragma("unroll") for (int _i = 0; _i < 2; ++_i) \
;         __builtin_amdgcn_global_load_lds((const unsigned*)((const char*)(gbase) + (voff)[_i]), (LAS unsigned*)(lds + (bufoff) + ldsw + _i * 8192), 16, 0, 0); } while (0)
; #define PG8_LDA(dst, b, h) do { _Pragma("unroll") for (int m = 0; m < 4; ++m) _Pragma("unroll") for (int k = 0; k < 2; ++k) dst[m][k] = *(const LAS bf16x8*)(lds + PG8_SA(b, h) + aoff + m * 2048 + k * 1024); } while (0)
; #define PG8_LDB(dst, b, h) do { _Pragma("unroll") for (int n = 0; n < 2; ++n) _Pragma("unroll") for (int k = 0; k < 2; ++k) dst[n][k] = *(const LAS bf16x8*)(lds + PG8_SB(b, h) + boff + n * 2048 + k * 1024); } while (0)
; #define PG8_MMA(ai, bj, At, Bt) do { __builtin_amdgcn_s_setprio(1); _Pragma("unroll") for (int m = 0; m < 4; ++m) _Pragma("unroll") for (int n = 0; n < 2; ++n) _Pragma("unroll") for (int k = 0; k < 2; ++k) \
;         acc[ai][bj][m][n] = __builtin_amdgcn_mfma_f32_16x16x32_bf16(Bt[n][k], At[m][k], acc[ai][bj][m][n], 0, 0, 0); __builtin_amdgcn_s_setprio(0); } while (0)
; #define PG8_WAIT_V(n) asm volatile("s_waitcnt vmcnt(" #n ")" ::: "memory")
; #define PG8_WAIT_L(n) asm volatile("s_waitcnt lgkmcnt(" #n ")" ::: "memory")
; #define PG8_BAR __builtin_amdgcn_s_barrier()
; #define PG8_SCHED __builtin_amdgcn_sched_barrier(0)
; template <class Epi, class Sched>
; __device__ __forceinline__ void gemm_phase(LAS unsigned char* lds, const Gemm g, const Sched& S, const Epi& E) {
;     ...
;         for (int t = 0; t < nt; t += 2) {
;             const bool last = (t == nt - 2);
;             const char* a1 = cA + (size_t)(t + 1) * kstep;
;             const char* a2 = last ? nA : cA + (size_t)(t + 2) * kstep; const char* b2 = last ? nB : cB + (size_t)(t + 2) * kstep;
;             const char* a3 = a2 + kstep; const char* b3 = b2 + kstep;
;             PG8_LDB(B0, 0, 0); PG8_LDB(B1, 0, 1); PG8_SCHED; PG8_LDA(At, 0, 0); PG8_STAGE(PG8_SA(1, 1), a1 + hstepA, voffA);
;             PG8_WAIT_V(8); PG8_WAIT_L(0); PG8_BAR; PG8_MMA(0, 0, At, B0); PG8_MMA(0, 1, At, B1); PG8_BAR; PG8_SCHED;
;             PG8_LDA(At, 0, 1); PG8_STAGE(PG8_SB(0, 0), b2, voffB); PG8_STAGE(PG8_SB(0, 1), b2 + hstepB, voffB); PG8_STAGE(PG8_SA(0, 0), a2, voffA);
.Ledge_p6:
.LBB0_724:
	s_add_u32 s48, s62, 0xfff80080
	s_addc_u32 s49, s63, -1
	s_add_i32 s83, 0, 0x10000
	s_cmp_eq_u32 s75, 28
	s_cselect_b32 s67, s2, s49
	s_cselect_b32 s66, s34, s48
	v_add_u32_e32 v161, s83, v159
	s_cselect_b32 s65, s35, s53
	s_cselect_b32 s64, s39, s45
	s_add_i32 s84, 0, 0x14000
	ds_read_b128 v[146:149], v161
	ds_read_b128 v[162:165], v161 offset:1024
	ds_read_b128 v[166:169], v161 offset:2048
	ds_read_b128 v[170:173], v161 offset:3072
	v_add_u32_e32 v161, s84, v159
	ds_read_b128 v[174:177], v161
	ds_read_b128 v[178:181], v161 offset:1024
	ds_read_b128 v[182:185], v161 offset:2048
	ds_read_b128 v[186:189], v161 offset:3072
	v_lshl_add_u64 v[222:223], s[62:63], 0, v[138:139]
	s_add_i32 m0, s61, 0xc000
	ds_read_b128 v[190:193], v160
	ds_read_b128 v[194:197], v160 offset:1024
	ds_read_b128 v[198:201], v160 offset:2048
	ds_read_b128 v[202:205], v160 offset:3072
	ds_read_b128 v[206:209], v160 offset:4096
	ds_read_b128 v[210:213], v160 offset:5120
	ds_read_b128 v[214:217], v160 offset:6144
	ds_read_b128 v[218:221], v160 offset:7168
	global_load_lds_dwordx4 v[222:223], off
	v_lshl_add_u64 v[222:223], s[62:63], 0, v[140:141]
	s_add_i32 m0, s61, 0xe000
	s_nop 0
	global_load_lds_dwordx4 v[222:223], off
	s_waitcnt vmcnt(8)
	s_waitcnt lgkmcnt(0)
	s_barrier
	s_setprio 1
	s_waitcnt lgkmcnt(0)
	v_mfma_f32_16x16x32_bf16 v[124:127], v[146:149], v[190:193], v[124:127]
	v_mfma_f32_16x16x32_bf16 v[120:123], v[166:169], v[190:193], v[120:123]
	v_mfma_f32_16x16x32_bf16 v[108:111], v[146:149], v[198:201], v[108:111]
	v_mfma_f32_16x16x32_bf16 v[104:107], v[166:169], v[198:201], v[104:107]
	v_mfma_f32_16x16x32_bf16 v[92:95], v[146:149], v[206:209], v[92:95]
	v_mfma_f32_16x16x32_bf16 v[88:91], v[166:169], v[206:209], v[88:91]
	v_mfma_f32_16x16x32_bf16 v[76:79], v[146:149], v[214:217], v[76:79]
	v_mfma_f32_16x16x32_bf16 v[72:75], v[166:169], v[214:217], v[72:75]
	v_mfma_f32_16x16x32_bf16 v[124:127], v[162:165], v[194:197], v[124:127]
	v_mfma_f32_16x16x32_bf16 v[120:123], v[170:173], v[194:197], v[120:123]
	v_mfma_f32_16x16x32_bf16 v[108:111], v[162:165], v[202:205], v[108:111]
	v_mfma_f32_16x16x32_bf16 v[104:107], v[170:173], v[202:205], v[104:107]
	v_mfma_f32_16x16x32_bf16 v[92:95], v[162:165], v[210:213], v[92:95]
	v_mfma_f32_16x16x32_bf16 v[88:91], v[170:173], v[210:213], v[88:91]
	v_mfma_f32_16x16x32_bf16 v[76:79], v[162:165], v[218:221], v[76:79]
	v_mfma_f32_16x16x32_bf16 v[72:75], v[170:173], v[218:221], v[72:75]
	s_setprio 0
	s_setprio 1
	v_mfma_f32_16x16x32_bf16 v[116:119], v[174:177], v[190:193], v[116:119]
	v_mfma_f32_16x16x32_bf16 v[112:115], v[182:185], v[190:193], v[112:115]
	v_mfma_f32_16x16x32_bf16 v[100:103], v[174:177], v[198:201], v[100:103]
	v_mfma_f32_16x16x32_bf16 v[96:99], v[182:185], v[198:201], v[96:99]
	v_mfma_f32_16x16x32_bf16 v[84:87], v[174:177], v[206:209], v[84:87]
	v_mfma_f32_16x16x32_bf16 v[80:83], v[182:185], v[206:209], v[80:83]
	v_mfma_f32_16x16x32_bf16 v[68:71], v[174:177], v[214:217], v[68:71]
	v_mfma_f32_16x16x32_bf16 v[64:67], v[182:185], v[214:217], v[64:67]
	v_mfma_f32_16x16x32_bf16 v[116:119], v[178:181], v[194:197], v[116:119]
	v_mfma_f32_16x16x32_bf16 v[112:115], v[186:189], v[194:197], v[112:115]
	v_mfma_f32_16x16x32_bf16 v[100:103], v[178:181], v[202:205], v[100:103]
	v_mfma_f32_16x16x32_bf16 v[96:99], v[186:189], v[202:205], v[96:99]
	v_mfma_f32_16x16x32_bf16 v[84:87], v[178:181], v[210:213], v[84:87]
	v_mfma_f32_16x16x32_bf16 v[80:83], v[186:189], v[210:213], v[80:83]
	v_mfma_f32_16x16x32_bf16 v[68:71], v[178:181], v[218:221], v[68:71]
	v_mfma_f32_16x16x32_bf16 v[64:67], v[186:189], v[218:221], v[64:67]
	s_setprio 0
	s_barrier
	s_add_i32 s48, s83, s76
	v_lshl_add_u64 v[222:223], s[64:65], 0, v[130:131]
	s_mov_b32 m0, s48
	ds_read_b128 v[190:193], v160 offset:16384
	ds_read_b128 v[194:197], v160 offset:17408
	ds_read_b128 v[198:201], v160 offset:18432
	ds_read_b128 v[202:205], v160 offset:19456
	ds_read_b128 v[206:209], v160 offset:20480
	ds_read_b128 v[210:213], v160 offset:21504
	ds_read_b128 v[214:217], v160 offset:22528
	ds_read_b128 v[218:221], v160 offset:23552
	global_load_lds_dwordx4 v[222:223], off
	s_add_i32 m0, s48, 0x2000
	s_add_u32 s48, s64, 0x80000
	v_lshl_add_u64 v[224:225], s[64:65], 0, v[134:135]
	s_addc_u32 s49, s65, 0
	s_add_i32 s83, s84, s76
	global_load_lds_dwordx4 v[224:225], off
	v_lshl_add_u64 v[226:227], s[48:49], 0, v[130:131]
	s_mov_b32 m0, s83
	v_lshl_add_u64 v[228:229], s[66:67], 0, v[132:133]
	global_load_lds_dwordx4 v[226:227], off
	v_lshl_add_u64 v[226:227], s[48:49], 0, v[134:135]
	s_add_i32 m0, s83, 0x2000
	s_nop 0
	global_load_lds_dwordx4 v[226:227], off
	v_lshl_add_u64 v[226:227], s[66:67], 0, v[128:129]
	s_mov_b32 m0, s61
	s_nop 0
	global_load_lds_dwordx4 v[226:227], off
	s_mov_b32 m0, s77
	s_nop 0
	global_load_lds_dwordx4 v[228:229], off
	s_waitcnt vmcnt(8)
	s_waitcnt lgkmcnt(0)
	s_barrier
; #define PG8_STAGE(bufoff, gbase, voff) do { _Pragma("unroll") for (int _i = 0; _i < 2; ++_i) \
;         __builtin_amdgcn_global_load_lds((const unsigned*)((const char*)(gbase) + (voff)[_i]), (LAS unsigned*)(lds + (bufoff) + ldsw + _i * 8192), 16, 0, 0); } while (0)
; #define PG8_LDA(dst, b, h) do { _Pragma("unroll") for (int m = 0; m < 4; ++m) _Pragma("unroll") for (int k = 0; k < 2; ++k) dst[m][k] = *(const LAS bf16x8*)(lds + PG8_SA(b, h) + aoff + m * 2048 + k * 1024); } while (0)
; #define PG8_LDB(dst, b, h) do { _Pragma("unroll") for (int n = 0; n < 2; ++n) _Pragma("unroll") for (int k = 0; k < 2; ++k) dst[n][k] = *(const LAS bf16x8*)(lds + PG8_SB(b, h) + boff + n * 2048 + k * 1024); } while (0)
; #define PG8_MMA(ai, bj, At, Bt) do { __builtin_amdgcn_s_setprio(1); _Pragma("unroll") for (int m = 0; m < 4; ++m) _Pragma("unroll") for (int n = 0; n < 2; ++n) _Pragma("unroll") for (int k = 0; k < 2; ++k) \
;         acc[ai][bj][m][n] = __builtin_amdgcn_mfma_f32_16x16x32_bf16(Bt[n][k], At[m][k], acc[ai][bj][m][n], 0, 0, 0); __builtin_amdgcn_s_setprio(0); } while (0)
; #define PG8_WAIT_V(n) asm volatile("s_waitcnt vmcnt(" #n ")" ::: "memory")
; #define PG8_WAIT_L(n) asm volatile("s_waitcnt lgkmcnt(" #n ")" ::: "memory")
; #define PG8_BAR __builtin_amdgcn_s_barrier()
; #define PG8_SCHED __builtin_amdgcn_sched_barrier(0)
; template <class Epi, class Sched>
; __device__ __forceinline__ void gemm_phase(LAS unsigned char* lds, const Gemm g, const Sched& S, const Epi& E) {
;     ...
;             PG8_WAIT_V(8); PG8_WAIT_L(0); PG8_BAR; PG8_MMA(1, 0, At, B0); PG8_MMA(1, 1, At, B1); PG8_BAR; PG8_SCHED;
;             PG8_LDB(B0, 1, 0); PG8_LDB(B1, 1, 1); PG8_SCHED; PG8_LDA(At, 1, 0); PG8_STAGE(PG8_SA(0, 1), a2 + hstepA, voffA);
;             PG8_WAIT_V(8); PG8_WAIT_L(0); PG8_BAR; PG8_MMA(0, 0, At, B0); PG8_MMA(0, 1, At, B1); PG8_BAR; PG8_SCHED;
	s_setprio 1
	s_waitcnt lgkmcnt(0)
	v_mfma_f32_16x16x32_bf16 v[60:63], v[146:149], v[190:193], v[60:63]
	v_mfma_f32_16x16x32_bf16 v[56:59], v[166:169], v[190:193], v[56:59]
	v_mfma_f32_16x16x32_bf16 v[44:47], v[146:149], v[198:201], v[44:47]
	v_mfma_f32_16x16x32_bf16 v[40:43], v[166:169], v[198:201], v[40:43]
	v_mfma_f32_16x16x32_bf16 v[28:31], v[146:149], v[206:209], v[28:31]
	v_mfma_f32_16x16x32_bf16 v[24:27], v[166:169], v[206:209], v[24:27]
	v_mfma_f32_16x16x32_bf16 v[12:15], v[146:149], v[214:217], v[12:15]
	v_mfma_f32_16x16x32_bf16 v[8:11], v[166:169], v[214:217], v[8:11]
	v_mfma_f32_16x16x32_bf16 v[60:63], v[162:165], v[194:197], v[60:63]
	v_mfma_f32_16x16x32_bf16 v[56:59], v[170:173], v[194:197], v[56:59]
	v_mfma_f32_16x16x32_bf16 v[44:47], v[162:165], v[202:205], v[44:47]
	v_mfma_f32_16x16x32_bf16 v[40:43], v[170:173], v[202:205], v[40:43]
	v_mfma_f32_16x16x32_bf16 v[28:31], v[162:165], v[210:213], v[28:31]
	v_mfma_f32_16x16x32_bf16 v[24:27], v[170:173], v[210:213], v[24:27]
	v_mfma_f32_16x16x32_bf16 v[12:15], v[162:165], v[218:221], v[12:15]
	v_mfma_f32_16x16x32_bf16 v[8:11], v[170:173], v[218:221], v[8:11]
	s_setprio 0
	s_setprio 1
	v_mfma_f32_16x16x32_bf16 v[52:55], v[174:177], v[190:193], v[52:55]
	v_mfma_f32_16x16x32_bf16 v[48:51], v[182:185], v[190:193], v[48:51]
	v_mfma_f32_16x16x32_bf16 v[36:39], v[174:177], v[198:201], v[36:39]
	v_mfma_f32_16x16x32_bf16 v[32:35], v[182:185], v[198:201], v[32:35]
	v_mfma_f32_16x16x32_bf16 v[20:23], v[174:177], v[206:209], v[20:23]
	v_mfma_f32_16x16x32_bf16 v[16:19], v[182:185], v[206:209], v[16:19]
	v_mfma_f32_16x16x32_bf16 v[4:7], v[174:177], v[214:217], v[4:7]
	v_mfma_f32_16x16x32_bf16 v[0:3], v[182:185], v[214:217], v[0:3]
	v_mfma_f32_16x16x32_bf16 v[52:55], v[178:181], v[194:197], v[52:55]
	v_mfma_f32_16x16x32_bf16 v[48:51], v[186:189], v[194:197], v[48:51]
	v_mfma_f32_16x16x32_bf16 v[36:39], v[178:181], v[202:205], v[36:39]
	v_mfma_f32_16x16x32_bf16 v[32:35], v[186:189], v[202:205], v[32:35]
	v_mfma_f32_16x16x32_bf16 v[20:23], v[178:181], v[210:213], v[20:23]
	v_mfma_f32_16x16x32_bf16 v[16:19], v[186:189], v[210:213], v[16:19]
	v_mfma_f32_16x16x32_bf16 v[4:7], v[178:181], v[218:221], v[4:7]
	v_mfma_f32_16x16x32_bf16 v[0:3], v[186:189], v[218:221], v[0:3]
	s_setprio 0
	s_barrier
	s_add_i32 s83, 0, 0x18000
	v_add_u32_e32 v161, s83, v159
	s_add_i32 s84, 0, 0x1c000
	ds_read_b128 v[146:149], v161
	ds_read_b128 v[162:165], v161 offset:1024
	ds_read_b128 v[166:169], v161 offset:2048
	ds_read_b128 v[170:173], v161 offset:3072
	v_add_u32_e32 v161, s84, v159
	ds_read_b128 v[174:177], v161
	ds_read_b128 v[178:181], v161 offset:1024
	ds_read_b128 v[182:185], v161 offset:2048
	ds_read_b128 v[186:189], v161 offset:3072
	s_add_u32 s48, s66, 0x80000
	s_addc_u32 s49, s67, 0
	s_mov_b32 m0, s78
	v_lshl_add_u64 v[230:231], s[48:49], 0, v[128:129]
	ds_read_b128 v[190:193], v160 offset:32768
	ds_read_b128 v[194:197], v160 offset:33792
	ds_read_b128 v[198:201], v160 offset:34816
	ds_read_b128 v[202:205], v160 offset:35840
	ds_read_b128 v[206:209], v160 offset:36864
	ds_read_b128 v[210:213], v160 offset:37888
	ds_read_b128 v[214:217], v160 offset:38912
	ds_read_b128 v[218:221], v160 offset:39936
	global_load_lds_dwordx4 v[230:231], off
	v_lshl_add_u64 v[230:231], s[48:49], 0, v[132:133]
	s_mov_b32 m0, s79
	s_nop 0
	global_load_lds_dwordx4 v[230:231], off
	s_waitcnt vmcnt(8)
	s_waitcnt lgkmcnt(0)
	s_barrier
	s_setprio 1
	s_waitcnt lgkmcnt(0)
	v_mfma_f32_16x16x32_bf16 v[124:127], v[146:149], v[190:193], v[124:127]
	v_mfma_f32_16x16x32_bf16 v[120:123], v[166:169], v[190:193], v[120:123]
	v_mfma_f32_16x16x32_bf16 v[108:111], v[146:149], v[198:201], v[108:111]
	v_mfma_f32_16x16x32_bf16 v[104:107], v[166:169], v[198:201], v[104:107]
	v_mfma_f32_16x16x32_bf16 v[92:95], v[146:149], v[206:209], v[92:95]
	v_mfma_f32_16x16x32_bf16 v[88:91], v[166:169], v[206:209], v[88:91]
	v_mfma_f32_16x16x32_bf16 v[76:79], v[146:149], v[214:217], v[76:79]
	v_mfma_f32_16x16x32_bf16 v[72:75], v[166:169], v[214:217], v[72:75]
	v_mfma_f32_16x16x32_bf16 v[124:127], v[162:165], v[194:197], v[124:127]
	v_mfma_f32_16x16x32_bf16 v[120:123], v[170:173], v[194:197], v[120:123]
	v_mfma_f32_16x16x32_bf16 v[108:111], v[162:165], v[202:205], v[108:111]
	v_mfma_f32_16x16x32_bf16 v[104:107], v[170:173], v[202:205], v[104:107]
	v_mfma_f32_16x16x32_bf16 v[92:95], v[162:165], v[210:213], v[92:95]
	v_mfma_f32_16x16x32_bf16 v[88:91], v[170:173], v[210:213], v[88:91]
	v_mfma_f32_16x16x32_bf16 v[76:79], v[162:165], v[218:221], v[76:79]
	v_mfma_f32_16x16x32_bf16 v[72:75], v[170:173], v[218:221], v[72:75]
	s_setprio 0
	s_setprio 1
	v_mfma_f32_16x16x32_bf16 v[116:119], v[174:177], v[190:193], v[116:119]
	v_mfma_f32_16x16x32_bf16 v[112:115], v[182:185], v[190:193], v[112:115]
	v_mfma_f32_16x16x32_bf16 v[100:103], v[174:177], v[198:201], v[100:103]
	v_mfma_f32_16x16x32_bf16 v[96:99], v[182:185], v[198:201], v[96:99]
	v_mfma_f32_16x16x32_bf16 v[84:87], v[174:177], v[206:209], v[84:87]
	v_mfma_f32_16x16x32_bf16 v[80:83], v[182:185], v[206:209], v[80:83]
	v_mfma_f32_16x16x32_bf16 v[68:71], v[174:177], v[214:217], v[68:71]
	v_mfma_f32_16x16x32_bf16 v[64:67], v[182:185], v[214:217], v[64:67]
	v_mfma_f32_16x16x32_bf16 v[116:119], v[178:181], v[194:197], v[116:119]
	v_mfma_f32_16x16x32_bf16 v[112:115], v[186:189], v[194:197], v[112:115]
	v_mfma_f32_16x16x32_bf16 v[100:103], v[178:181], v[202:205], v[100:103]
	v_mfma_f32_16x16x32_bf16 v[96:99], v[186:189], v[202:205], v[96:99]
	v_mfma_f32_16x16x32_bf16 v[84:87], v[178:181], v[210:213], v[84:87]
	v_mfma_f32_16x16x32_bf16 v[80:83], v[186:189], v[210:213], v[80:83]
	v_mfma_f32_16x16x32_bf16 v[68:71], v[178:181], v[218:221], v[68:71]
	v_mfma_f32_16x16x32_bf16 v[64:67], v[186:189], v[218:221], v[64:67]
	s_setprio 0
	s_barrier
; #define PG8_STAGE(bufoff, gbase, voff) do { _Pragma("unroll") for (int _i = 0; _i < 2; ++_i) \
;         __builtin_amdgcn_global_load_lds((const unsigned*)((const char*)(gbase) + (voff)[_i]), (LAS unsigned*)(lds + (bufoff) + ldsw + _i * 8192), 16, 0, 0); } while (0)
; #define PG8_LDA(dst, b, h) do { _Pragma("unroll") for (int m = 0; m < 4; ++m) _Pragma("unroll") for (int k = 0; k < 2; ++k) dst[m][k] = *(const LAS bf16x8*)(lds + PG8_SA(b, h) + aoff + m * 2048 + k * 1024); } while (0)
; #define PG8_MMA(ai, bj, At, Bt) do { __builtin_amdgcn_s_setprio(1); _Pragma("unroll") for (int m = 0; m < 4; ++m) _Pragma("unroll") for (int n = 0; n < 2; ++n) _Pragma("unroll") for (int k = 0; k < 2; ++k) \
;         acc[ai][bj][m][n] = __builtin_amdgcn_mfma_f32_16x16x32_bf16(Bt[n][k], At[m][k], acc[ai][bj][m][n], 0, 0, 0); __builtin_amdgcn_s_setprio(0); } while (0)
; #define PG8_WAIT_V(n) asm volatile("s_waitcnt vmcnt(" #n ")" ::: "memory")
; #define PG8_WAIT_L(n) asm volatile("s_waitcnt lgkmcnt(" #n ")" ::: "memory")
; #define PG8_BAR __builtin_amdgcn_s_barrier()
; #define PG8_SCHED __builtin_amdgcn_sched_barrier(0)
; template <class Epi, class Sched>
; __device__ __forceinline__ void gemm_phase(LAS unsigned char* lds, const Gemm g, const Sched& S, const Epi& E) {
;     ...
;             PG8_LDA(At, 1, 1); PG8_STAGE(PG8_SB(1, 0), b3, voffB); PG8_STAGE(PG8_SB(1, 1), b3 + hstepB, voffB); PG8_STAGE(PG8_SA(1, 0), a3, voffA);
;             PG8_WAIT_V(8); PG8_WAIT_L(0); PG8_BAR; PG8_MMA(1, 0, At, B0); PG8_MMA(1, 1, At, B1); PG8_BAR; PG8_SCHED;
;         }
	s_add_i32 s48, s83, s76
	v_lshl_add_u64 v[222:223], v[222:223], 0, s[22:23]
	s_mov_b32 m0, s48
	ds_read_b128 v[190:193], v160 offset:49152
	ds_read_b128 v[194:197], v160 offset:50176
	ds_read_b128 v[198:201], v160 offset:51200
	ds_read_b128 v[202:205], v160 offset:52224
	ds_read_b128 v[206:209], v160 offset:53248
	ds_read_b128 v[210:213], v160 offset:54272
	ds_read_b128 v[214:217], v160 offset:55296
	ds_read_b128 v[218:221], v160 offset:56320
	global_load_lds_dwordx4 v[222:223], off
	s_add_i32 m0, s48, 0x2000
	s_add_u32 s48, s64, 0x80080
	v_lshl_add_u64 v[222:223], v[224:225], 0, s[22:23]
	s_addc_u32 s49, s65, 0
	s_add_i32 s64, s84, s76
	global_load_lds_dwordx4 v[222:223], off
	v_lshl_add_u64 v[222:223], s[48:49], 0, v[130:131]
	s_mov_b32 m0, s64
	s_nop 0
	global_load_lds_dwordx4 v[222:223], off
	v_lshl_add_u64 v[222:223], s[48:49], 0, v[134:135]
	s_add_i32 m0, s64, 0x2000
	s_nop 0
	global_load_lds_dwordx4 v[222:223], off
	v_lshl_add_u64 v[222:223], v[226:227], 0, s[22:23]
	s_mov_b32 m0, s80
	s_nop 0
	global_load_lds_dwordx4 v[222:223], off
	v_lshl_add_u64 v[222:223], v[228:229], 0, s[22:23]
	s_mov_b32 m0, s81
	s_nop 0
	global_load_lds_dwordx4 v[222:223], off
	s_waitcnt vmcnt(8)
	s_waitcnt lgkmcnt(0)
	s_barrier
	s_setprio 1
	s_waitcnt lgkmcnt(0)
	v_mfma_f32_16x16x32_bf16 v[60:63], v[146:149], v[190:193], v[60:63]
	v_mfma_f32_16x16x32_bf16 v[56:59], v[166:169], v[190:193], v[56:59]
	v_mfma_f32_16x16x32_bf16 v[44:47], v[146:149], v[198:201], v[44:47]
	v_mfma_f32_16x16x32_bf16 v[40:43], v[166:169], v[198:201], v[40:43]
	v_mfma_f32_16x16x32_bf16 v[28:31], v[146:149], v[206:209], v[28:31]
	v_mfma_f32_16x16x32_bf16 v[24:27], v[166:169], v[206:209], v[24:27]
	v_mfma_f32_16x16x32_bf16 v[12:15], v[146:149], v[214:217], v[12:15]
	v_mfma_f32_16x16x32_bf16 v[8:11], v[166:169], v[214:217], v[8:11]
	v_mfma_f32_16x16x32_bf16 v[60:63], v[162:165], v[194:197], v[60:63]
	v_mfma_f32_16x16x32_bf16 v[56:59], v[170:173], v[194:197], v[56:59]
	v_mfma_f32_16x16x32_bf16 v[44:47], v[162:165], v[202:205], v[44:47]
	v_mfma_f32_16x16x32_bf16 v[40:43], v[170:173], v[202:205], v[40:43]
	v_mfma_f32_16x16x32_bf16 v[28:31], v[162:165], v[210:213], v[28:31]
	v_mfma_f32_16x16x32_bf16 v[24:27], v[170:173], v[210:213], v[24:27]
	v_mfma_f32_16x16x32_bf16 v[12:15], v[162:165], v[218:221], v[12:15]
	v_mfma_f32_16x16x32_bf16 v[8:11], v[170:173], v[218:221], v[8:11]
	s_setprio 0
	s_setprio 1
	v_mfma_f32_16x16x32_bf16 v[52:55], v[174:177], v[190:193], v[52:55]
	v_mfma_f32_16x16x32_bf16 v[48:51], v[182:185], v[190:193], v[48:51]
	v_mfma_f32_16x16x32_bf16 v[36:39], v[174:177], v[198:201], v[36:39]
	v_mfma_f32_16x16x32_bf16 v[32:35], v[182:185], v[198:201], v[32:35]
	v_mfma_f32_16x16x32_bf16 v[20:23], v[174:177], v[206:209], v[20:23]
	v_mfma_f32_16x16x32_bf16 v[16:19], v[182:185], v[206:209], v[16:19]
	v_mfma_f32_16x16x32_bf16 v[4:7], v[174:177], v[214:217], v[4:7]
	v_mfma_f32_16x16x32_bf16 v[0:3], v[182:185], v[214:217], v[0:3]
	v_mfma_f32_16x16x32_bf16 v[52:55], v[178:181], v[194:197], v[52:55]
	v_mfma_f32_16x16x32_bf16 v[48:51], v[186:189], v[194:197], v[48:51]
	v_mfma_f32_16x16x32_bf16 v[36:39], v[178:181], v[202:205], v[36:39]
	v_mfma_f32_16x16x32_bf16 v[32:35], v[186:189], v[202:205], v[32:35]
	v_mfma_f32_16x16x32_bf16 v[20:23], v[178:181], v[210:213], v[20:23]
	v_mfma_f32_16x16x32_bf16 v[16:19], v[186:189], v[210:213], v[16:19]
	v_mfma_f32_16x16x32_bf16 v[4:7], v[178:181], v[218:221], v[4:7]
	v_mfma_f32_16x16x32_bf16 v[0:3], v[186:189], v[218:221], v[0:3]
	s_setprio 0
	s_add_i32 s75, s75, 2
	s_add_u32 s62, s62, 0x100
	s_addc_u32 s63, s63, 0
	s_add_u32 s45, s45, 0x100
	s_addc_u32 s53, s53, 0
	s_cmp_gt_u32 s75, 29
	s_barrier
	s_cbranch_scc0 .LBB0_724
	s_and_b64 vcc, exec, s[42:43]
	s_cbranch_vccz .LBB0_727
	s_barrier

; #define PG8_STAGE(bufoff, gbase, voff) do { _Pragma("unroll") for (int _i = 0; _i < 2; ++_i) \
;         __builtin_amdgcn_global_load_lds((const unsigned*)((const char*)(gbase) + (voff)[_i]), (LAS unsigned*)(lds + (bufoff) + ldsw + _i * 8192), 16, 0, 0); } while (0)
; #define PG8_LDA(dst, b, h) do { _Pragma("unroll") for (int m = 0; m < 4; ++m) _Pragma("unroll") for (int k = 0; k < 2; ++k) dst[m][k] = *(const LAS bf16x8*)(lds + PG8_SA(b, h) + aoff + m * 2048 + k * 1024); } while (0)
; #define PG8_LDB(dst, b, h) do { _Pragma("unroll") for (int n = 0; n < 2; ++n) _Pragma("unroll") for (int k = 0; k < 2; ++k) dst[n][k] = *(const LAS bf16x8*)(lds + PG8_SB(b, h) + boff + n * 2048 + k * 1024); } while (0)
; #define PG8_MMA(ai, bj, At, Bt) do { __builtin_amdgcn_s_setprio(1); _Pragma("unroll") for (int m = 0; m < 4; ++m) _Pragma("unroll") for (int n = 0; n < 2; ++n) _Pragma("unroll") for (int k = 0; k < 2; ++k) \
;         acc[ai][bj][m][n] = __builtin_amdgcn_mfma_f32_16x16x32_bf16(Bt[n][k], At[m][k], acc[ai][bj][m][n], 0, 0, 0); __builtin_amdgcn_s_setprio(0); } while (0)
; #define PG8_WAIT_V(n) asm volatile("s_waitcnt vmcnt(" #n ")" ::: "memory")
; #define PG8_WAIT_L(n) asm volatile("s_waitcnt lgkmcnt(" #n ")" ::: "memory")
; #define PG8_BAR __builtin_amdgcn_s_barrier()
; #define PG8_SCHED __builtin_amdgcn_sched_barrier(0)
; template <class Epi, class Sched>
; __device__ __forceinline__ void gemm_phase(LAS unsigned char* lds, const Gemm g, const Sched& S, const Epi& E) {
;     ...
;         for (int t = 0; t < nt; t += 2) {
;             const bool last = (t == nt - 2);
;             const char* a1 = cA + (size_t)(t + 1) * kstep;
;             const char* a2 = last ? nA : cA + (size_t)(t + 2) * kstep; const char* b2 = last ? nB : cB + (size_t)(t + 2) * kstep;
;             const char* a3 = a2 + kstep; const char* b3 = b2 + kstep;
;             PG8_LDB(B0, 0, 0); PG8_LDB(B1, 0, 1); PG8_SCHED; PG8_LDA(At, 0, 0); PG8_STAGE(PG8_SA(1, 1), a1 + hstepA, voffA);
;             PG8_WAIT_V(8); PG8_WAIT_L(0); PG8_BAR; PG8_MMA(0, 0, At, B0); PG8_MMA(0, 1, At, B1); PG8_BAR; PG8_SCHED;
;             PG8_LDA(At, 0, 1); PG8_STAGE(PG8_SB(0, 0), b2, voffB); PG8_STAGE(PG8_SB(0, 1), b2 + hstepB, voffB); PG8_STAGE(PG8_SA(0, 0), a2, voffA);
.Ledge_p7:
.LBB0_837:
	ds_read_b128 v[146:149], v155
	ds_read_b128 v[160:163], v155 offset:1024
	ds_read_b128 v[164:167], v155 offset:2048
	ds_read_b128 v[168:171], v155 offset:3072
	ds_read_b128 v[172:175], v156
	ds_read_b128 v[176:179], v156 offset:1024
	ds_read_b128 v[180:183], v156 offset:2048
	ds_read_b128 v[184:187], v156 offset:3072
	s_add_u32 s38, s36, 0xfff80800
	s_addc_u32 s39, s37, -1
	s_cmp_eq_u32 s55, 28
	s_cselect_b32 s41, s19, s39
	s_cselect_b32 s40, s51, s38
	s_cselect_b32 s39, s17, s54
	s_cselect_b32 s38, s52, s53
	v_lshl_add_u64 v[150:151], s[36:37], 0, v[138:139]
	s_add_i32 m0, s25, 0xc000
	ds_read_b128 v[188:191], v157
	ds_read_b128 v[192:195], v157 offset:1024
	ds_read_b128 v[196:199], v157 offset:2048
	ds_read_b128 v[200:203], v157 offset:3072
	ds_read_b128 v[204:207], v157 offset:4096
	ds_read_b128 v[208:211], v157 offset:5120
	ds_read_b128 v[212:215], v157 offset:6144
	ds_read_b128 v[216:219], v157 offset:7168
	global_load_lds_dwordx4 v[150:151], off
	v_lshl_add_u64 v[150:151], s[36:37], 0, v[140:141]
	s_add_i32 m0, s25, 0xe000
	s_nop 0
	global_load_lds_dwordx4 v[150:151], off
	s_waitcnt vmcnt(8)
	s_waitcnt lgkmcnt(0)
	s_barrier
	s_setprio 1
	s_waitcnt lgkmcnt(0)
	v_mfma_f32_16x16x32_bf16 v[124:127], v[146:149], v[188:191], v[124:127]
	v_mfma_f32_16x16x32_bf16 v[120:123], v[164:167], v[188:191], v[120:123]
	v_mfma_f32_16x16x32_bf16 v[108:111], v[146:149], v[196:199], v[108:111]
	v_mfma_f32_16x16x32_bf16 v[104:107], v[164:167], v[196:199], v[104:107]
	v_mfma_f32_16x16x32_bf16 v[92:95], v[146:149], v[204:207], v[92:95]
	v_mfma_f32_16x16x32_bf16 v[88:91], v[164:167], v[204:207], v[88:91]
	v_mfma_f32_16x16x32_bf16 v[76:79], v[146:149], v[212:215], v[76:79]
	v_mfma_f32_16x16x32_bf16 v[72:75], v[164:167], v[212:215], v[72:75]
	v_mfma_f32_16x16x32_bf16 v[124:127], v[160:163], v[192:195], v[124:127]
	v_mfma_f32_16x16x32_bf16 v[120:123], v[168:171], v[192:195], v[120:123]
	v_mfma_f32_16x16x32_bf16 v[108:111], v[160:163], v[200:203], v[108:111]
	v_mfma_f32_16x16x32_bf16 v[104:107], v[168:171], v[200:203], v[104:107]
	v_mfma_f32_16x16x32_bf16 v[92:95], v[160:163], v[208:211], v[92:95]
	v_mfma_f32_16x16x32_bf16 v[88:91], v[168:171], v[208:211], v[88:91]
	v_mfma_f32_16x16x32_bf16 v[76:79], v[160:163], v[216:219], v[76:79]
	v_mfma_f32_16x16x32_bf16 v[72:75], v[168:171], v[216:219], v[72:75]
	s_setprio 0
	s_setprio 1
	v_mfma_f32_16x16x32_bf16 v[116:119], v[172:175], v[188:191], v[116:119]
	v_mfma_f32_16x16x32_bf16 v[112:115], v[180:183], v[188:191], v[112:115]
	v_mfma_f32_16x16x32_bf16 v[100:103], v[172:175], v[196:199], v[100:103]
	v_mfma_f32_16x16x32_bf16 v[96:99], v[180:183], v[196:199], v[96:99]
	v_mfma_f32_16x16x32_bf16 v[84:87], v[172:175], v[204:207], v[84:87]
	v_mfma_f32_16x16x32_bf16 v[80:83], v[180:183], v[204:207], v[80:83]
	v_mfma_f32_16x16x32_bf16 v[68:71], v[172:175], v[212:215], v[68:71]
	v_mfma_f32_16x16x32_bf16 v[64:67], v[180:183], v[212:215], v[64:67]
	v_mfma_f32_16x16x32_bf16 v[116:119], v[176:179], v[192:195], v[116:119]
	v_mfma_f32_16x16x32_bf16 v[112:115], v[184:187], v[192:195], v[112:115]
	v_mfma_f32_16x16x32_bf16 v[100:103], v[176:179], v[200:203], v[100:103]
	v_mfma_f32_16x16x32_bf16 v[96:99], v[184:187], v[200:203], v[96:99]
	v_mfma_f32_16x16x32_bf16 v[84:87], v[176:179], v[208:211], v[84:87]
	v_mfma_f32_16x16x32_bf16 v[80:83], v[184:187], v[208:211], v[80:83]
	v_mfma_f32_16x16x32_bf16 v[68:71], v[176:179], v[216:219], v[68:71]
	v_mfma_f32_16x16x32_bf16 v[64:67], v[184:187], v[216:219], v[64:67]
	s_setprio 0
	s_barrier
	s_add_i32 s48, s46, s5
	v_lshl_add_u64 v[150:151], s[38:39], 0, v[130:131]
	s_mov_b32 m0, s48
	ds_read_b128 v[188:191], v157 offset:16384
	ds_read_b128 v[192:195], v157 offset:17408
	ds_read_b128 v[196:199], v157 offset:18432
	ds_read_b128 v[200:203], v157 offset:19456
	ds_read_b128 v[204:207], v157 offset:20480
	ds_read_b128 v[208:211], v157 offset:21504
	ds_read_b128 v[212:215], v157 offset:22528
	ds_read_b128 v[216:219], v157 offset:23552
	global_load_lds_dwordx4 v[150:151], off
	s_add_i32 m0, s48, 0x2000
	s_add_u32 s48, s38, 0x80000
	v_lshl_add_u64 v[220:221], s[38:39], 0, v[134:135]
	s_addc_u32 s49, s39, 0
	s_add_i32 s56, s47, s5
	global_load_lds_dwordx4 v[220:221], off
	v_lshl_add_u64 v[222:223], s[48:49], 0, v[130:131]
	s_mov_b32 m0, s56
	v_lshl_add_u64 v[224:225], s[40:41], 0, v[132:133]
	global_load_lds_dwordx4 v[222:223], off
	v_lshl_add_u64 v[222:223], s[48:49], 0, v[134:135]
	s_add_i32 m0, s56, 0x2000
	s_nop 0
	global_load_lds_dwordx4 v[222:223], off
	v_lshl_add_u64 v[222:223], s[40:41], 0, v[128:129]
	s_mov_b32 m0, s25
	s_nop 0
	global_load_lds_dwordx4 v[222:223], off
	s_mov_b32 m0, s33
	s_nop 0
	global_load_lds_dwordx4 v[224:225], off
	s_waitcnt vmcnt(8)
	s_waitcnt lgkmcnt(0)
	s_barrier
; #define PG8_STAGE(bufoff, gbase, voff) do { _Pragma("unroll") for (int _i = 0; _i < 2; ++_i) \
;         __builtin_amdgcn_global_load_lds((const unsigned*)((const char*)(gbase) + (voff)[_i]), (LAS unsigned*)(lds + (bufoff) + ldsw + _i * 8192), 16, 0, 0); } while (0)
; #define PG8_LDA(dst, b, h) do { _Pragma("unroll") for (int m = 0; m < 4; ++m) _Pragma("unroll") for (int k = 0; k < 2; ++k) dst[m][k] = *(const LAS bf16x8*)(lds + PG8_SA(b, h) + aoff + m * 2048 + k * 1024); } while (0)
; #define PG8_LDB(dst, b, h) do { _Pragma("unroll") for (int n = 0; n < 2; ++n) _Pragma("unroll") for (int k = 0; k < 2; ++k) dst[n][k] = *(const LAS bf16x8*)(lds + PG8_SB(b, h) + boff + n * 2048 + k * 1024); } while (0)
; #define PG8_MMA(ai, bj, At, Bt) do { __builtin_amdgcn_s_setprio(1); _Pragma("unroll") for (int m = 0; m < 4; ++m) _Pragma("unroll") for (int n = 0; n < 2; ++n) _Pragma("unroll") for (int k = 0; k < 2; ++k) \
;         acc[ai][bj][m][n] = __builtin_amdgcn_mfma_f32_16x16x32_bf16(Bt[n][k], At[m][k], acc[ai][bj][m][n], 0, 0, 0); __builtin_amdgcn_s_setprio(0); } while (0)
; #define PG8_WAIT_V(n) asm volatile("s_waitcnt vmcnt(" #n ")" ::: "memory")
; #define PG8_WAIT_L(n) asm volatile("s_waitcnt lgkmcnt(" #n ")" ::: "memory")
; #define PG8_BAR __builtin_amdgcn_s_barrier()
; #define PG8_SCHED __builtin_amdgcn_sched_barrier(0)
; template <class Epi, class Sched>
; __device__ __forceinline__ void gemm_phase(LAS unsigned char* lds, const Gemm g, const Sched& S, const Epi& E) {
;     ...
;             PG8_WAIT_V(8); PG8_WAIT_L(0); PG8_BAR; PG8_MMA(1, 0, At, B0); PG8_MMA(1, 1, At, B1); PG8_BAR; PG8_SCHED;
;             PG8_LDB(B0, 1, 0); PG8_LDB(B1, 1, 1); PG8_SCHED; PG8_LDA(At, 1, 0); PG8_STAGE(PG8_SA(0, 1), a2 + hstepA, voffA);
;             PG8_WAIT_V(8); PG8_WAIT_L(0); PG8_BAR; PG8_MMA(0, 0, At, B0); PG8_MMA(0, 1, At, B1); PG8_BAR; PG8_SCHED;
	s_setprio 1
	s_waitcnt lgkmcnt(0)
	v_mfma_f32_16x16x32_bf16 v[60:63], v[146:149], v[188:191], v[60:63]
	v_mfma_f32_16x16x32_bf16 v[56:59], v[164:167], v[188:191], v[56:59]
	v_mfma_f32_16x16x32_bf16 v[44:47], v[146:149], v[196:199], v[44:47]
	v_mfma_f32_16x16x32_bf16 v[40:43], v[164:167], v[196:199], v[40:43]
	v_mfma_f32_16x16x32_bf16 v[28:31], v[146:149], v[204:207], v[28:31]
	v_mfma_f32_16x16x32_bf16 v[24:27], v[164:167], v[204:207], v[24:27]
	v_mfma_f32_16x16x32_bf16 v[12:15], v[146:149], v[212:215], v[12:15]
	v_mfma_f32_16x16x32_bf16 v[8:11], v[164:167], v[212:215], v[8:11]
	v_mfma_f32_16x16x32_bf16 v[60:63], v[160:163], v[192:195], v[60:63]
	v_mfma_f32_16x16x32_bf16 v[56:59], v[168:171], v[192:195], v[56:59]
	v_mfma_f32_16x16x32_bf16 v[44:47], v[160:163], v[200:203], v[44:47]
	v_mfma_f32_16x16x32_bf16 v[40:43], v[168:171], v[200:203], v[40:43]
	v_mfma_f32_16x16x32_bf16 v[28:31], v[160:163], v[208:211], v[28:31]
	v_mfma_f32_16x16x32_bf16 v[24:27], v[168:171], v[208:211], v[24:27]
	v_mfma_f32_16x16x32_bf16 v[12:15], v[160:163], v[216:219], v[12:15]
	v_mfma_f32_16x16x32_bf16 v[8:11], v[168:171], v[216:219], v[8:11]
	s_setprio 0
	s_setprio 1
	v_mfma_f32_16x16x32_bf16 v[52:55], v[172:175], v[188:191], v[52:55]
	v_mfma_f32_16x16x32_bf16 v[48:51], v[180:183], v[188:191], v[48:51]
	v_mfma_f32_16x16x32_bf16 v[36:39], v[172:175], v[196:199], v[36:39]
	v_mfma_f32_16x16x32_bf16 v[32:35], v[180:183], v[196:199], v[32:35]
	v_mfma_f32_16x16x32_bf16 v[20:23], v[172:175], v[204:207], v[20:23]
	v_mfma_f32_16x16x32_bf16 v[16:19], v[180:183], v[204:207], v[16:19]
	v_mfma_f32_16x16x32_bf16 v[4:7], v[172:175], v[212:215], v[4:7]
	v_mfma_f32_16x16x32_bf16 v[0:3], v[180:183], v[212:215], v[0:3]
	v_mfma_f32_16x16x32_bf16 v[52:55], v[176:179], v[192:195], v[52:55]
	v_mfma_f32_16x16x32_bf16 v[48:51], v[184:187], v[192:195], v[48:51]
	v_mfma_f32_16x16x32_bf16 v[36:39], v[176:179], v[200:203], v[36:39]
	v_mfma_f32_16x16x32_bf16 v[32:35], v[184:187], v[200:203], v[32:35]
	v_mfma_f32_16x16x32_bf16 v[20:23], v[176:179], v[208:211], v[20:23]
	v_mfma_f32_16x16x32_bf16 v[16:19], v[184:187], v[208:211], v[16:19]
	v_mfma_f32_16x16x32_bf16 v[4:7], v[176:179], v[216:219], v[4:7]
	v_mfma_f32_16x16x32_bf16 v[0:3], v[184:187], v[216:219], v[0:3]
	s_setprio 0
	s_barrier
	s_add_i32 s48, 0, 0x18000
	v_add_u32_e32 v159, s48, v153
	s_add_i32 s49, 0, 0x1c000
	ds_read_b128 v[146:149], v159
	ds_read_b128 v[160:163], v159 offset:1024
	ds_read_b128 v[164:167], v159 offset:2048
	ds_read_b128 v[168:171], v159 offset:3072
	v_add_u32_e32 v159, s49, v153
	ds_read_b128 v[172:175], v159
	ds_read_b128 v[176:179], v159 offset:1024
	ds_read_b128 v[180:183], v159 offset:2048
	ds_read_b128 v[184:187], v159 offset:3072
	s_add_u32 s40, s40, 0x80000
	s_addc_u32 s41, s41, 0
	s_mov_b32 m0, s34
	v_lshl_add_u64 v[226:227], s[40:41], 0, v[128:129]
	ds_read_b128 v[188:191], v157 offset:32768
	ds_read_b128 v[192:195], v157 offset:33792
	ds_read_b128 v[196:199], v157 offset:34816
	ds_read_b128 v[200:203], v157 offset:35840
	ds_read_b128 v[204:207], v157 offset:36864
	ds_read_b128 v[208:211], v157 offset:37888
	ds_read_b128 v[212:215], v157 offset:38912
	ds_read_b128 v[216:219], v157 offset:39936
	global_load_lds_dwordx4 v[226:227], off
	v_lshl_add_u64 v[226:227], s[40:41], 0, v[132:133]
	s_mov_b32 m0, s35
	s_nop 0
	global_load_lds_dwordx4 v[226:227], off
	s_waitcnt vmcnt(8)
	s_waitcnt lgkmcnt(0)
	s_barrier
	s_setprio 1
	s_waitcnt lgkmcnt(0)
	v_mfma_f32_16x16x32_bf16 v[124:127], v[146:149], v[188:191], v[124:127]
	v_mfma_f32_16x16x32_bf16 v[120:123], v[164:167], v[188:191], v[120:123]
	v_mfma_f32_16x16x32_bf16 v[108:111], v[146:149], v[196:199], v[108:111]
	v_mfma_f32_16x16x32_bf16 v[104:107], v[164:167], v[196:199], v[104:107]
	v_mfma_f32_16x16x32_bf16 v[92:95], v[146:149], v[204:207], v[92:95]
	v_mfma_f32_16x16x32_bf16 v[88:91], v[164:167], v[204:207], v[88:91]
	v_mfma_f32_16x16x32_bf16 v[76:79], v[146:149], v[212:215], v[76:79]
	v_mfma_f32_16x16x32_bf16 v[72:75], v[164:167], v[212:215], v[72:75]
	v_mfma_f32_16x16x32_bf16 v[124:127], v[160:163], v[192:195], v[124:127]
	v_mfma_f32_16x16x32_bf16 v[120:123], v[168:171], v[192:195], v[120:123]
	v_mfma_f32_16x16x32_bf16 v[108:111], v[160:163], v[200:203], v[108:111]
	v_mfma_f32_16x16x32_bf16 v[104:107], v[168:171], v[200:203], v[104:107]
	v_mfma_f32_16x16x32_bf16 v[92:95], v[160:163], v[208:211], v[92:95]
	v_mfma_f32_16x16x32_bf16 v[88:91], v[168:171], v[208:211], v[88:91]
	v_mfma_f32_16x16x32_bf16 v[76:79], v[160:163], v[216:219], v[76:79]
	v_mfma_f32_16x16x32_bf16 v[72:75], v[168:171], v[216:219], v[72:75]
	s_setprio 0
	s_setprio 1
	v_mfma_f32_16x16x32_bf16 v[116:119], v[172:175], v[188:191], v[116:119]
	v_mfma_f32_16x16x32_bf16 v[112:115], v[180:183], v[188:191], v[112:115]
	v_mfma_f32_16x16x32_bf16 v[100:103], v[172:175], v[196:199], v[100:103]
	v_mfma_f32_16x16x32_bf16 v[96:99], v[180:183], v[196:199], v[96:99]
	v_mfma_f32_16x16x32_bf16 v[84:87], v[172:175], v[204:207], v[84:87]
	v_mfma_f32_16x16x32_bf16 v[80:83], v[180:183], v[204:207], v[80:83]
	v_mfma_f32_16x16x32_bf16 v[68:71], v[172:175], v[212:215], v[68:71]
	v_mfma_f32_16x16x32_bf16 v[64:67], v[180:183], v[212:215], v[64:67]
	v_mfma_f32_16x16x32_bf16 v[116:119], v[176:179], v[192:195], v[116:119]
	v_mfma_f32_16x16x32_bf16 v[112:115], v[184:187], v[192:195], v[112:115]
	v_mfma_f32_16x16x32_bf16 v[100:103], v[176:179], v[200:203], v[100:103]
	v_mfma_f32_16x16x32_bf16 v[96:99], v[184:187], v[200:203], v[96:99]
	v_mfma_f32_16x16x32_bf16 v[84:87], v[176:179], v[208:211], v[84:87]
	v_mfma_f32_16x16x32_bf16 v[80:83], v[184:187], v[208:211], v[80:83]
	v_mfma_f32_16x16x32_bf16 v[68:71], v[176:179], v[216:219], v[68:71]
	v_mfma_f32_16x16x32_bf16 v[64:67], v[184:187], v[216:219], v[64:67]
	s_setprio 0
	s_barrier
; #define PG8_STAGE(bufoff, gbase, voff) do { _Pragma("unroll") for (int _i = 0; _i < 2; ++_i) \
;         __builtin_amdgcn_global_load_lds((const unsigned*)((const char*)(gbase) + (voff)[_i]), (LAS unsigned*)(lds + (bufoff) + ldsw + _i * 8192), 16, 0, 0); } while (0)
; #define PG8_LDA(dst, b, h) do { _Pragma("unroll") for (int m = 0; m < 4; ++m) _Pragma("unroll") for (int k = 0; k < 2; ++k) dst[m][k] = *(const LAS bf16x8*)(lds + PG8_SA(b, h) + aoff + m * 2048 + k * 1024); } while (0)
; #define PG8_MMA(ai, bj, At, Bt) do { __builtin_amdgcn_s_setprio(1); _Pragma("unroll") for (int m = 0; m < 4; ++m) _Pragma("unroll") for (int n = 0; n < 2; ++n) _Pragma("unroll") for (int k = 0; k < 2; ++k) \
;         acc[ai][bj][m][n] = __builtin_amdgcn_mfma_f32_16x16x32_bf16(Bt[n][k], At[m][k], acc[ai][bj][m][n], 0, 0, 0); __builtin_amdgcn_s_setprio(0); } while (0)
; #define PG8_WAIT_V(n) asm volatile("s_waitcnt vmcnt(" #n ")" ::: "memory")
; #define PG8_WAIT_L(n) asm volatile("s_waitcnt lgkmcnt(" #n ")" ::: "memory")
; #define PG8_BAR __builtin_amdgcn_s_barrier()
; #define PG8_SCHED __builtin_amdgcn_sched_barrier(0)
; template <class Epi, class Sched>
; __device__ __forceinline__ void gemm_phase(LAS unsigned char* lds, const Gemm g, const Sched& S, const Epi& E) {
;     ...
;             PG8_LDA(At, 1, 1); PG8_STAGE(PG8_SB(1, 0), b3, voffB); PG8_STAGE(PG8_SB(1, 1), b3 + hstepB, voffB); PG8_STAGE(PG8_SA(1, 0), a3, voffA);
;             PG8_WAIT_V(8); PG8_WAIT_L(0); PG8_BAR; PG8_MMA(1, 0, At, B0); PG8_MMA(1, 1, At, B1); PG8_BAR; PG8_SCHED;
;         }
	s_add_i32 s40, s48, s5
	v_lshl_add_u64 v[150:151], v[150:151], 0, s[10:11]
	s_mov_b32 m0, s40
	ds_read_b128 v[188:191], v157 offset:49152
	ds_read_b128 v[192:195], v157 offset:50176
	ds_read_b128 v[196:199], v157 offset:51200
	ds_read_b128 v[200:203], v157 offset:52224
	ds_read_b128 v[204:207], v157 offset:53248
	ds_read_b128 v[208:211], v157 offset:54272
	ds_read_b128 v[212:215], v157 offset:55296
	ds_read_b128 v[216:219], v157 offset:56320
	global_load_lds_dwordx4 v[150:151], off
	s_add_i32 m0, s40, 0x2000
	s_add_u32 s38, s38, 0x80080
	v_lshl_add_u64 v[150:151], v[220:221], 0, s[10:11]
	s_addc_u32 s39, s39, 0
	s_add_i32 s40, s49, s5
	global_load_lds_dwordx4 v[150:151], off
	v_lshl_add_u64 v[150:151], s[38:39], 0, v[130:131]
	s_mov_b32 m0, s40
	s_nop 0
	global_load_lds_dwordx4 v[150:151], off
	v_lshl_add_u64 v[150:151], s[38:39], 0, v[134:135]
	s_add_i32 m0, s40, 0x2000
	s_nop 0
	global_load_lds_dwordx4 v[150:151], off
	v_lshl_add_u64 v[150:151], v[222:223], 0, s[98:99]
	s_mov_b32 m0, s43
	s_nop 0
	global_load_lds_dwordx4 v[150:151], off
	v_lshl_add_u64 v[150:151], v[224:225], 0, s[98:99]
	s_mov_b32 m0, s44
	s_nop 0
	global_load_lds_dwordx4 v[150:151], off
	s_waitcnt vmcnt(8)
	s_waitcnt lgkmcnt(0)
	s_barrier
	s_setprio 1
	s_waitcnt lgkmcnt(0)
	v_mfma_f32_16x16x32_bf16 v[60:63], v[146:149], v[188:191], v[60:63]
	v_mfma_f32_16x16x32_bf16 v[56:59], v[164:167], v[188:191], v[56:59]
	v_mfma_f32_16x16x32_bf16 v[44:47], v[146:149], v[196:199], v[44:47]
	v_mfma_f32_16x16x32_bf16 v[40:43], v[164:167], v[196:199], v[40:43]
	v_mfma_f32_16x16x32_bf16 v[28:31], v[146:149], v[204:207], v[28:31]
	v_mfma_f32_16x16x32_bf16 v[24:27], v[164:167], v[204:207], v[24:27]
	v_mfma_f32_16x16x32_bf16 v[12:15], v[146:149], v[212:215], v[12:15]
	v_mfma_f32_16x16x32_bf16 v[8:11], v[164:167], v[212:215], v[8:11]
	v_mfma_f32_16x16x32_bf16 v[60:63], v[160:163], v[192:195], v[60:63]
	v_mfma_f32_16x16x32_bf16 v[56:59], v[168:171], v[192:195], v[56:59]
	v_mfma_f32_16x16x32_bf16 v[44:47], v[160:163], v[200:203], v[44:47]
	v_mfma_f32_16x16x32_bf16 v[40:43], v[168:171], v[200:203], v[40:43]
	v_mfma_f32_16x16x32_bf16 v[28:31], v[160:163], v[208:211], v[28:31]
	v_mfma_f32_16x16x32_bf16 v[24:27], v[168:171], v[208:211], v[24:27]
	v_mfma_f32_16x16x32_bf16 v[12:15], v[160:163], v[216:219], v[12:15]
	v_mfma_f32_16x16x32_bf16 v[8:11], v[168:171], v[216:219], v[8:11]
	s_setprio 0
	s_setprio 1
	v_mfma_f32_16x16x32_bf16 v[52:55], v[172:175], v[188:191], v[52:55]
	v_mfma_f32_16x16x32_bf16 v[48:51], v[180:183], v[188:191], v[48:51]
	v_mfma_f32_16x16x32_bf16 v[36:39], v[172:175], v[196:199], v[36:39]
	v_mfma_f32_16x16x32_bf16 v[32:35], v[180:183], v[196:199], v[32:35]
	v_mfma_f32_16x16x32_bf16 v[20:23], v[172:175], v[204:207], v[20:23]
	v_mfma_f32_16x16x32_bf16 v[16:19], v[180:183], v[204:207], v[16:19]
	v_mfma_f32_16x16x32_bf16 v[4:7], v[172:175], v[212:215], v[4:7]
	v_mfma_f32_16x16x32_bf16 v[0:3], v[180:183], v[212:215], v[0:3]
	v_mfma_f32_16x16x32_bf16 v[52:55], v[176:179], v[192:195], v[52:55]
	v_mfma_f32_16x16x32_bf16 v[48:51], v[184:187], v[192:195], v[48:51]
	v_mfma_f32_16x16x32_bf16 v[36:39], v[176:179], v[200:203], v[36:39]
	v_mfma_f32_16x16x32_bf16 v[32:35], v[184:187], v[200:203], v[32:35]
	v_mfma_f32_16x16x32_bf16 v[20:23], v[176:179], v[208:211], v[20:23]
	v_mfma_f32_16x16x32_bf16 v[16:19], v[184:187], v[208:211], v[16:19]
	v_mfma_f32_16x16x32_bf16 v[4:7], v[176:179], v[216:219], v[4:7]
	v_mfma_f32_16x16x32_bf16 v[0:3], v[184:187], v[216:219], v[0:3]
	s_setprio 0
	s_add_i32 s55, s55, 2
	s_add_u32 s36, s36, 0x1000
	s_addc_u32 s37, s37, 0
	s_add_u32 s53, s53, 0x100
	s_addc_u32 s54, s54, 0
	s_cmp_gt_u32 s55, 29
	s_barrier
	s_cbranch_scc0 .LBB0_837
	s_and_b64 vcc, exec, s[12:13]
	s_cbranch_vccz .LBB0_840
	s_barrier

; #define PG8_STAGE(bufoff, gbase, voff) do { _Pragma("unroll") for (int _i = 0; _i < 2; ++_i) \
;         __builtin_amdgcn_global_load_lds((const unsigned*)((const char*)(gbase) + (voff)[_i]), (LAS unsigned*)(lds + (bufoff) + ldsw + _i * 8192), 16, 0, 0); } while (0)
; #define PG8_LDA(dst, b, h) do { _Pragma("unroll") for (int m = 0; m < 4; ++m) _Pragma("unroll") for (int k = 0; k < 2; ++k) dst[m][k] = *(const LAS bf16x8*)(lds + PG8_SA(b, h) + aoff + m * 2048 + k * 1024); } while (0)
; #define PG8_LDB(dst, b, h) do { _Pragma("unroll") for (int n = 0; n < 2; ++n) _Pragma("unroll") for (int k = 0; k < 2; ++k) dst[n][k] = *(const LAS bf16x8*)(lds + PG8_SB(b, h) + boff + n * 2048 + k * 1024); } while (0)
; #define PG8_MMA(ai, bj, At, Bt) do { __builtin_amdgcn_s_setprio(1); _Pragma("unroll") for (int m = 0; m < 4; ++m) _Pragma("unroll") for (int n = 0; n < 2; ++n) _Pragma("unroll") for (int k = 0; k < 2; ++k) \
;         acc[ai][bj][m][n] = __builtin_amdgcn_mfma_f32_16x16x32_bf16(Bt[n][k], At[m][k], acc[ai][bj][m][n], 0, 0, 0); __builtin_amdgcn_s_setprio(0); } while (0)
; #define PG8_WAIT_V(n) asm volatile("s_waitcnt vmcnt(" #n ")" ::: "memory")
; #define PG8_WAIT_L(n) asm volatile("s_waitcnt lgkmcnt(" #n ")" ::: "memory")
; #define PG8_BAR __builtin_amdgcn_s_barrier()
; #define PG8_SCHED __builtin_amdgcn_sched_barrier(0)
; template <class Epi, class Sched>
; __device__ __forceinline__ void gemm_phase(LAS unsigned char* lds, const Gemm g, const Sched& S, const Epi& E) {
;     ...
;         for (int t = 0; t < nt; t += 2) {
;             const bool last = (t == nt - 2);
;             const char* a1 = cA + (size_t)(t + 1) * kstep;
;             const char* a2 = last ? nA : cA + (size_t)(t + 2) * kstep; const char* b2 = last ? nB : cB + (size_t)(t + 2) * kstep;
;             const char* a3 = a2 + kstep; const char* b3 = b2 + kstep;
;             PG8_LDB(B0, 0, 0); PG8_LDB(B1, 0, 1); PG8_SCHED; PG8_LDA(At, 0, 0); PG8_STAGE(PG8_SA(1, 1), a1 + hstepA, voffA);
;             PG8_WAIT_V(8); PG8_WAIT_L(0); PG8_BAR; PG8_MMA(0, 0, At, B0); PG8_MMA(0, 1, At, B1); PG8_BAR; PG8_SCHED;
;             PG8_LDA(At, 0, 1); PG8_STAGE(PG8_SB(0, 0), b2, voffB); PG8_STAGE(PG8_SB(0, 1), b2 + hstepB, voffB); PG8_STAGE(PG8_SA(0, 0), a2, voffA);
.Ledge_p8:
.LBB0_917:
	ds_read_b128 v[128:131], v208
	ds_read_b128 v[132:135], v208 offset:1024
	ds_read_b128 v[136:139], v208 offset:2048
	ds_read_b128 v[140:143], v208 offset:3072
	ds_read_b128 v[144:147], v209
	ds_read_b128 v[148:151], v209 offset:1024
	ds_read_b128 v[172:175], v209 offset:2048
	ds_read_b128 v[176:179], v209 offset:3072
	s_add_i32 s55, s47, 2
	s_add_u32 s57, s8, 0xffe00800
	s_addc_u32 s59, s9, -1
	s_cmp_eq_u32 s35, s47
	s_cselect_b32 s71, s2, s59
	s_cselect_b32 s70, s5, s57
	s_cselect_b32 s67, s19, s46
	s_cselect_b32 s66, s34, s41
	v_lshl_add_u64 v[216:217], s[8:9], 0, v[168:169]
	s_add_i32 m0, s17, 0xc000
	ds_read_b128 v[180:183], v210
	ds_read_b128 v[184:187], v210 offset:1024
	ds_read_b128 v[188:191], v210 offset:2048
	ds_read_b128 v[192:195], v210 offset:3072
	ds_read_b128 v[196:199], v210 offset:4096
	ds_read_b128 v[200:203], v210 offset:5120
	ds_read_b128 v[204:207], v210 offset:6144
	ds_read_b128 v[212:215], v210 offset:7168
	global_load_lds_dwordx4 v[216:217], off
	v_lshl_add_u64 v[216:217], s[8:9], 0, v[170:171]
	s_add_i32 m0, s17, 0xe000
	s_nop 0
	global_load_lds_dwordx4 v[216:217], off
	s_waitcnt vmcnt(8)
	s_waitcnt lgkmcnt(0)
	s_barrier
	s_setprio 1
	s_waitcnt lgkmcnt(0)
	v_mfma_f32_16x16x32_bf16 v[124:127], v[128:131], v[180:183], v[124:127]
	v_mfma_f32_16x16x32_bf16 v[120:123], v[136:139], v[180:183], v[120:123]
	v_mfma_f32_16x16x32_bf16 v[116:119], v[128:131], v[188:191], v[116:119]
	v_mfma_f32_16x16x32_bf16 v[112:115], v[136:139], v[188:191], v[112:115]
	v_mfma_f32_16x16x32_bf16 v[104:107], v[128:131], v[196:199], v[104:107]
	v_mfma_f32_16x16x32_bf16 v[96:99], v[136:139], v[196:199], v[96:99]
	v_mfma_f32_16x16x32_bf16 v[88:91], v[128:131], v[204:207], v[88:91]
	v_mfma_f32_16x16x32_bf16 v[80:83], v[136:139], v[204:207], v[80:83]
	v_mfma_f32_16x16x32_bf16 v[124:127], v[132:135], v[184:187], v[124:127]
	v_mfma_f32_16x16x32_bf16 v[120:123], v[140:143], v[184:187], v[120:123]
	v_mfma_f32_16x16x32_bf16 v[116:119], v[132:135], v[192:195], v[116:119]
	v_mfma_f32_16x16x32_bf16 v[112:115], v[140:143], v[192:195], v[112:115]
	v_mfma_f32_16x16x32_bf16 v[104:107], v[132:135], v[200:203], v[104:107]
	v_mfma_f32_16x16x32_bf16 v[96:99], v[140:143], v[200:203], v[96:99]
	v_mfma_f32_16x16x32_bf16 v[88:91], v[132:135], v[212:215], v[88:91]
	v_mfma_f32_16x16x32_bf16 v[80:83], v[140:143], v[212:215], v[80:83]
	s_setprio 0
	s_setprio 1
	v_mfma_f32_16x16x32_bf16 v[108:111], v[144:147], v[180:183], v[108:111]
	v_mfma_f32_16x16x32_bf16 v[100:103], v[172:175], v[180:183], v[100:103]
	v_mfma_f32_16x16x32_bf16 v[92:95], v[144:147], v[188:191], v[92:95]
	v_mfma_f32_16x16x32_bf16 v[84:87], v[172:175], v[188:191], v[84:87]
	v_mfma_f32_16x16x32_bf16 v[76:79], v[144:147], v[196:199], v[76:79]
	v_mfma_f32_16x16x32_bf16 v[72:75], v[172:175], v[196:199], v[72:75]
	v_mfma_f32_16x16x32_bf16 v[68:71], v[144:147], v[204:207], v[68:71]
	v_mfma_f32_16x16x32_bf16 v[64:67], v[172:175], v[204:207], v[64:67]
	v_mfma_f32_16x16x32_bf16 v[108:111], v[148:151], v[184:187], v[108:111]
	v_mfma_f32_16x16x32_bf16 v[100:103], v[176:179], v[184:187], v[100:103]
	v_mfma_f32_16x16x32_bf16 v[92:95], v[148:151], v[192:195], v[92:95]
	v_mfma_f32_16x16x32_bf16 v[84:87], v[176:179], v[192:195], v[84:87]
	v_mfma_f32_16x16x32_bf16 v[76:79], v[148:151], v[200:203], v[76:79]
	v_mfma_f32_16x16x32_bf16 v[72:75], v[176:179], v[200:203], v[72:75]
	v_mfma_f32_16x16x32_bf16 v[68:71], v[148:151], v[212:215], v[68:71]
	v_mfma_f32_16x16x32_bf16 v[64:67], v[176:179], v[212:215], v[64:67]
	s_setprio 0
	s_barrier
	s_add_i32 s47, s81, s39
	v_lshl_add_u64 v[216:217], s[66:67], 0, v[156:157]
	s_mov_b32 m0, s47
	ds_read_b128 v[180:183], v210 offset:16384
	ds_read_b128 v[184:187], v210 offset:17408
	ds_read_b128 v[188:191], v210 offset:18432
	ds_read_b128 v[192:195], v210 offset:19456
	ds_read_b128 v[196:199], v210 offset:20480
	ds_read_b128 v[200:203], v210 offset:21504
	ds_read_b128 v[204:207], v210 offset:22528
	ds_read_b128 v[212:215], v210 offset:23552
	global_load_lds_dwordx4 v[216:217], off
	s_add_i32 m0, s47, 0x2000
	s_add_u32 s90, s66, 0x200000
	v_lshl_add_u64 v[218:219], s[66:67], 0, v[160:161]
	s_addc_u32 s91, s67, 0
	s_add_i32 s47, s82, s39
	global_load_lds_dwordx4 v[218:219], off
	v_lshl_add_u64 v[220:221], s[90:91], 0, v[156:157]
	s_mov_b32 m0, s47
	v_lshl_add_u64 v[222:223], s[70:71], 0, v[158:159]
	global_load_lds_dwordx4 v[220:221], off
	v_lshl_add_u64 v[220:221], s[90:91], 0, v[160:161]
	s_add_i32 m0, s47, 0x2000
	s_nop 0
	global_load_lds_dwordx4 v[220:221], off
	v_lshl_add_u64 v[220:221], s[70:71], 0, v[154:155]
	s_mov_b32 m0, s17
	s_nop 0
	global_load_lds_dwordx4 v[220:221], off
	s_mov_b32 m0, s72
	s_nop 0
	global_load_lds_dwordx4 v[222:223], off
	s_waitcnt vmcnt(8)
	s_waitcnt lgkmcnt(0)
	s_barrier
; #define PG8_STAGE(bufoff, gbase, voff) do { _Pragma("unroll") for (int _i = 0; _i < 2; ++_i) \
;         __builtin_amdgcn_global_load_lds((const unsigned*)((const char*)(gbase) + (voff)[_i]), (LAS unsigned*)(lds + (bufoff) + ldsw + _i * 8192), 16, 0, 0); } while (0)
; #define PG8_LDA(dst, b, h) do { _Pragma("unroll") for (int m = 0; m < 4; ++m) _Pragma("unroll") for (int k = 0; k < 2; ++k) dst[m][k] = *(const LAS bf16x8*)(lds + PG8_SA(b, h) + aoff + m * 2048 + k * 1024); } while (0)
; #define PG8_LDB(dst, b, h) do { _Pragma("unroll") for (int n = 0; n < 2; ++n) _Pragma("unroll") for (int k = 0; k < 2; ++k) dst[n][k] = *(const LAS bf16x8*)(lds + PG8_SB(b, h) + boff + n * 2048 + k * 1024); } while (0)
; #define PG8_MMA(ai, bj, At, Bt) do { __builtin_amdgcn_s_setprio(1); _Pragma("unroll") for (int m = 0; m < 4; ++m) _Pragma("unroll") for (int n = 0; n < 2; ++n) _Pragma("unroll") for (int k = 0; k < 2; ++k) \
;         acc[ai][bj][m][n] = __builtin_amdgcn_mfma_f32_16x16x32_bf16(Bt[n][k], At[m][k], acc[ai][bj][m][n], 0, 0, 0); __builtin_amdgcn_s_setprio(0); } while (0)
; #define PG8_WAIT_V(n) asm volatile("s_waitcnt vmcnt(" #n ")" ::: "memory")
; #define PG8_WAIT_L(n) asm volatile("s_waitcnt lgkmcnt(" #n ")" ::: "memory")
; #define PG8_BAR __builtin_amdgcn_s_barrier()
; #define PG8_SCHED __builtin_amdgcn_sched_barrier(0)
; template <class Epi, class Sched>
; __device__ __forceinline__ void gemm_phase(LAS unsigned char* lds, const Gemm g, const Sched& S, const Epi& E) {
;     ...
;             PG8_WAIT_V(8); PG8_WAIT_L(0); PG8_BAR; PG8_MMA(1, 0, At, B0); PG8_MMA(1, 1, At, B1); PG8_BAR; PG8_SCHED;
;             PG8_LDB(B0, 1, 0); PG8_LDB(B1, 1, 1); PG8_SCHED; PG8_LDA(At, 1, 0); PG8_STAGE(PG8_SA(0, 1), a2 + hstepA, voffA);
;             PG8_WAIT_V(8); PG8_WAIT_L(0); PG8_BAR; PG8_MMA(0, 0, At, B0); PG8_MMA(0, 1, At, B1); PG8_BAR; PG8_SCHED;
	s_setprio 1
	s_waitcnt lgkmcnt(0)
	v_mfma_f32_16x16x32_bf16 v[60:63], v[128:131], v[180:183], v[60:63]
	v_mfma_f32_16x16x32_bf16 v[56:59], v[136:139], v[180:183], v[56:59]
	v_mfma_f32_16x16x32_bf16 v[52:55], v[128:131], v[188:191], v[52:55]
	v_mfma_f32_16x16x32_bf16 v[48:51], v[136:139], v[188:191], v[48:51]
	v_mfma_f32_16x16x32_bf16 v[40:43], v[128:131], v[196:199], v[40:43]
	v_mfma_f32_16x16x32_bf16 v[32:35], v[136:139], v[196:199], v[32:35]
	v_mfma_f32_16x16x32_bf16 v[24:27], v[128:131], v[204:207], v[24:27]
	v_mfma_f32_16x16x32_bf16 v[16:19], v[136:139], v[204:207], v[16:19]
	v_mfma_f32_16x16x32_bf16 v[60:63], v[132:135], v[184:187], v[60:63]
	v_mfma_f32_16x16x32_bf16 v[56:59], v[140:143], v[184:187], v[56:59]
	v_mfma_f32_16x16x32_bf16 v[52:55], v[132:135], v[192:195], v[52:55]
	v_mfma_f32_16x16x32_bf16 v[48:51], v[140:143], v[192:195], v[48:51]
	v_mfma_f32_16x16x32_bf16 v[40:43], v[132:135], v[200:203], v[40:43]
	v_mfma_f32_16x16x32_bf16 v[32:35], v[140:143], v[200:203], v[32:35]
	v_mfma_f32_16x16x32_bf16 v[24:27], v[132:135], v[212:215], v[24:27]
	v_mfma_f32_16x16x32_bf16 v[16:19], v[140:143], v[212:215], v[16:19]
	s_setprio 0
	s_setprio 1
	v_mfma_f32_16x16x32_bf16 v[44:47], v[144:147], v[180:183], v[44:47]
	v_mfma_f32_16x16x32_bf16 v[36:39], v[172:175], v[180:183], v[36:39]
	v_mfma_f32_16x16x32_bf16 v[28:31], v[144:147], v[188:191], v[28:31]
	v_mfma_f32_16x16x32_bf16 v[20:23], v[172:175], v[188:191], v[20:23]
	v_mfma_f32_16x16x32_bf16 v[12:15], v[144:147], v[196:199], v[12:15]
	v_mfma_f32_16x16x32_bf16 v[8:11], v[172:175], v[196:199], v[8:11]
	v_mfma_f32_16x16x32_bf16 v[4:7], v[144:147], v[204:207], v[4:7]
	v_mfma_f32_16x16x32_bf16 v[0:3], v[172:175], v[204:207], v[0:3]
	v_mfma_f32_16x16x32_bf16 v[44:47], v[148:151], v[184:187], v[44:47]
	v_mfma_f32_16x16x32_bf16 v[36:39], v[176:179], v[184:187], v[36:39]
	v_mfma_f32_16x16x32_bf16 v[28:31], v[148:151], v[192:195], v[28:31]
	v_mfma_f32_16x16x32_bf16 v[20:23], v[176:179], v[192:195], v[20:23]
	v_mfma_f32_16x16x32_bf16 v[12:15], v[148:151], v[200:203], v[12:15]
	v_mfma_f32_16x16x32_bf16 v[8:11], v[176:179], v[200:203], v[8:11]
	v_mfma_f32_16x16x32_bf16 v[4:7], v[148:151], v[212:215], v[4:7]
	v_mfma_f32_16x16x32_bf16 v[0:3], v[176:179], v[212:215], v[0:3]
	s_setprio 0
	s_barrier
	s_add_i32 s47, 0, 0x18000
	s_add_i32 s57, 0, 0x1c000
	v_add_u32_e32 v140, s47, v153
	v_add_u32_e32 v176, s57, v153
	ds_read_b128 v[128:131], v140
	ds_read_b128 v[132:135], v140 offset:1024
	ds_read_b128 v[136:139], v140 offset:2048
	ds_read_b128 v[140:143], v140 offset:3072
	ds_read_b128 v[144:147], v176
	ds_read_b128 v[148:151], v176 offset:1024
	ds_read_b128 v[172:175], v176 offset:2048
	ds_read_b128 v[176:179], v176 offset:3072
	s_add_u32 s70, s70, 0x200000
	s_addc_u32 s71, s71, 0
	s_mov_b32 m0, s73
	v_lshl_add_u64 v[224:225], s[70:71], 0, v[154:155]
	ds_read_b128 v[180:183], v210 offset:32768
	ds_read_b128 v[184:187], v210 offset:33792
	ds_read_b128 v[188:191], v210 offset:34816
	ds_read_b128 v[192:195], v210 offset:35840
	ds_read_b128 v[196:199], v210 offset:36864
	ds_read_b128 v[200:203], v210 offset:37888
	ds_read_b128 v[204:207], v210 offset:38912
	ds_read_b128 v[212:215], v210 offset:39936
	global_load_lds_dwordx4 v[224:225], off
	v_lshl_add_u64 v[224:225], s[70:71], 0, v[158:159]
	s_mov_b32 m0, s76
	s_nop 0
	global_load_lds_dwordx4 v[224:225], off
	s_waitcnt vmcnt(8)
	s_waitcnt lgkmcnt(0)
	s_barrier
	s_setprio 1
	s_waitcnt lgkmcnt(0)
	v_mfma_f32_16x16x32_bf16 v[124:127], v[128:131], v[180:183], v[124:127]
	v_mfma_f32_16x16x32_bf16 v[120:123], v[136:139], v[180:183], v[120:123]
	v_mfma_f32_16x16x32_bf16 v[116:119], v[128:131], v[188:191], v[116:119]
	v_mfma_f32_16x16x32_bf16 v[112:115], v[136:139], v[188:191], v[112:115]
	v_mfma_f32_16x16x32_bf16 v[104:107], v[128:131], v[196:199], v[104:107]
	v_mfma_f32_16x16x32_bf16 v[96:99], v[136:139], v[196:199], v[96:99]
	v_mfma_f32_16x16x32_bf16 v[88:91], v[128:131], v[204:207], v[88:91]
	v_mfma_f32_16x16x32_bf16 v[80:83], v[136:139], v[204:207], v[80:83]
	v_mfma_f32_16x16x32_bf16 v[124:127], v[132:135], v[184:187], v[124:127]
	v_mfma_f32_16x16x32_bf16 v[120:123], v[140:143], v[184:187], v[120:123]
	v_mfma_f32_16x16x32_bf16 v[116:119], v[132:135], v[192:195], v[116:119]
	v_mfma_f32_16x16x32_bf16 v[112:115], v[140:143], v[192:195], v[112:115]
	v_mfma_f32_16x16x32_bf16 v[104:107], v[132:135], v[200:203], v[104:107]
	v_mfma_f32_16x16x32_bf16 v[96:99], v[140:143], v[200:203], v[96:99]
	v_mfma_f32_16x16x32_bf16 v[88:91], v[132:135], v[212:215], v[88:91]
	v_mfma_f32_16x16x32_bf16 v[80:83], v[140:143], v[212:215], v[80:83]
	s_setprio 0
	s_setprio 1
	v_mfma_f32_16x16x32_bf16 v[108:111], v[144:147], v[180:183], v[108:111]
	v_mfma_f32_16x16x32_bf16 v[100:103], v[172:175], v[180:183], v[100:103]
	v_mfma_f32_16x16x32_bf16 v[92:95], v[144:147], v[188:191], v[92:95]
	v_mfma_f32_16x16x32_bf16 v[84:87], v[172:175], v[188:191], v[84:87]
	v_mfma_f32_16x16x32_bf16 v[76:79], v[144:147], v[196:199], v[76:79]
	v_mfma_f32_16x16x32_bf16 v[72:75], v[172:175], v[196:199], v[72:75]
	v_mfma_f32_16x16x32_bf16 v[68:71], v[144:147], v[204:207], v[68:71]
	v_mfma_f32_16x16x32_bf16 v[64:67], v[172:175], v[204:207], v[64:67]
	v_mfma_f32_16x16x32_bf16 v[108:111], v[148:151], v[184:187], v[108:111]
	v_mfma_f32_16x16x32_bf16 v[100:103], v[176:179], v[184:187], v[100:103]
	v_mfma_f32_16x16x32_bf16 v[92:95], v[148:151], v[192:195], v[92:95]
	v_mfma_f32_16x16x32_bf16 v[84:87], v[176:179], v[192:195], v[84:87]
	v_mfma_f32_16x16x32_bf16 v[76:79], v[148:151], v[200:203], v[76:79]
	v_mfma_f32_16x16x32_bf16 v[72:75], v[176:179], v[200:203], v[72:75]
	v_mfma_f32_16x16x32_bf16 v[68:71], v[148:151], v[212:215], v[68:71]
	v_mfma_f32_16x16x32_bf16 v[64:67], v[176:179], v[212:215], v[64:67]
	s_setprio 0
	s_barrier
; #define PG8_STAGE(bufoff, gbase, voff) do { _Pragma("unroll") for (int _i = 0; _i < 2; ++_i) \
;         __builtin_amdgcn_global_load_lds((const unsigned*)((const char*)(gbase) + (voff)[_i]), (LAS unsigned*)(lds + (bufoff) + ldsw + _i * 8192), 16, 0, 0); } while (0)
; #define PG8_LDA(dst, b, h) do { _Pragma("unroll") for (int m = 0; m < 4; ++m) _Pragma("unroll") for (int k = 0; k < 2; ++k) dst[m][k] = *(const LAS bf16x8*)(lds + PG8_SA(b, h) + aoff + m * 2048 + k * 1024); } while (0)
; #define PG8_MMA(ai, bj, At, Bt) do { __builtin_amdgcn_s_setprio(1); _Pragma("unroll") for (int m = 0; m < 4; ++m) _Pragma("unroll") for (int n = 0; n < 2; ++n) _Pragma("unroll") for (int k = 0; k < 2; ++k) \
;         acc[ai][bj][m][n] = __builtin_amdgcn_mfma_f32_16x16x32_bf16(Bt[n][k], At[m][k], acc[ai][bj][m][n], 0, 0, 0); __builtin_amdgcn_s_setprio(0); } while (0)
; #define PG8_WAIT_V(n) asm volatile("s_waitcnt vmcnt(" #n ")" ::: "memory")
; #define PG8_WAIT_L(n) asm volatile("s_waitcnt lgkmcnt(" #n ")" ::: "memory")
; #define PG8_BAR __builtin_amdgcn_s_barrier()
; #define PG8_SCHED __builtin_amdgcn_sched_barrier(0)
; template <class Epi, class Sched>
; __device__ __forceinline__ void gemm_phase(LAS unsigned char* lds, const Gemm g, const Sched& S, const Epi& E) {
;     ...
;             PG8_LDA(At, 1, 1); PG8_STAGE(PG8_SB(1, 0), b3, voffB); PG8_STAGE(PG8_SB(1, 1), b3 + hstepB, voffB); PG8_STAGE(PG8_SA(1, 0), a3, voffA);
;             PG8_WAIT_V(8); PG8_WAIT_L(0); PG8_BAR; PG8_MMA(1, 0, At, B0); PG8_MMA(1, 1, At, B1); PG8_BAR; PG8_SCHED;
;         }
	s_add_i32 s47, s47, s39
	v_lshl_add_u64 v[216:217], v[216:217], 0, s[24:25]
	s_mov_b32 m0, s47
	ds_read_b128 v[180:183], v210 offset:49152
	ds_read_b128 v[184:187], v210 offset:50176
	ds_read_b128 v[188:191], v210 offset:51200
	ds_read_b128 v[192:195], v210 offset:52224
	ds_read_b128 v[196:199], v210 offset:53248
	ds_read_b128 v[200:203], v210 offset:54272
	ds_read_b128 v[204:207], v210 offset:55296
	ds_read_b128 v[212:215], v210 offset:56320
	global_load_lds_dwordx4 v[216:217], off
	s_add_i32 m0, s47, 0x2000
	s_add_u32 s66, s66, 0x200080
	v_lshl_add_u64 v[216:217], v[218:219], 0, s[24:25]
	s_addc_u32 s67, s67, 0
	s_add_i32 s47, s57, s39
	global_load_lds_dwordx4 v[216:217], off
	v_lshl_add_u64 v[216:217], s[66:67], 0, v[156:157]
	s_mov_b32 m0, s47
	s_nop 0
	global_load_lds_dwordx4 v[216:217], off
	v_lshl_add_u64 v[216:217], s[66:67], 0, v[160:161]
	s_add_i32 m0, s47, 0x2000
	s_nop 0
	global_load_lds_dwordx4 v[216:217], off
	v_lshl_add_u64 v[216:217], v[220:221], 0, s[98:99]
	s_mov_b32 m0, s79
	s_nop 0
	global_load_lds_dwordx4 v[216:217], off
	v_lshl_add_u64 v[216:217], v[222:223], 0, s[98:99]
	s_mov_b32 m0, s80
	s_nop 0
	global_load_lds_dwordx4 v[216:217], off
	s_waitcnt vmcnt(8)
	s_waitcnt lgkmcnt(0)
	s_barrier
	s_setprio 1
	s_waitcnt lgkmcnt(0)
	v_mfma_f32_16x16x32_bf16 v[60:63], v[128:131], v[180:183], v[60:63]
	v_mfma_f32_16x16x32_bf16 v[56:59], v[136:139], v[180:183], v[56:59]
	v_mfma_f32_16x16x32_bf16 v[52:55], v[128:131], v[188:191], v[52:55]
	v_mfma_f32_16x16x32_bf16 v[48:51], v[136:139], v[188:191], v[48:51]
	v_mfma_f32_16x16x32_bf16 v[40:43], v[128:131], v[196:199], v[40:43]
	v_mfma_f32_16x16x32_bf16 v[32:35], v[136:139], v[196:199], v[32:35]
	v_mfma_f32_16x16x32_bf16 v[24:27], v[128:131], v[204:207], v[24:27]
	v_mfma_f32_16x16x32_bf16 v[16:19], v[136:139], v[204:207], v[16:19]
	v_mfma_f32_16x16x32_bf16 v[60:63], v[132:135], v[184:187], v[60:63]
	v_mfma_f32_16x16x32_bf16 v[56:59], v[140:143], v[184:187], v[56:59]
	v_mfma_f32_16x16x32_bf16 v[52:55], v[132:135], v[192:195], v[52:55]
	v_mfma_f32_16x16x32_bf16 v[48:51], v[140:143], v[192:195], v[48:51]
	v_mfma_f32_16x16x32_bf16 v[40:43], v[132:135], v[200:203], v[40:43]
	v_mfma_f32_16x16x32_bf16 v[32:35], v[140:143], v[200:203], v[32:35]
	v_mfma_f32_16x16x32_bf16 v[24:27], v[132:135], v[212:215], v[24:27]
	v_mfma_f32_16x16x32_bf16 v[16:19], v[140:143], v[212:215], v[16:19]
	s_setprio 0
	s_setprio 1
	v_mfma_f32_16x16x32_bf16 v[44:47], v[144:147], v[180:183], v[44:47]
	v_mfma_f32_16x16x32_bf16 v[36:39], v[172:175], v[180:183], v[36:39]
	v_mfma_f32_16x16x32_bf16 v[28:31], v[144:147], v[188:191], v[28:31]
	v_mfma_f32_16x16x32_bf16 v[20:23], v[172:175], v[188:191], v[20:23]
	v_mfma_f32_16x16x32_bf16 v[12:15], v[144:147], v[196:199], v[12:15]
	v_mfma_f32_16x16x32_bf16 v[8:11], v[172:175], v[196:199], v[8:11]
	v_mfma_f32_16x16x32_bf16 v[4:7], v[144:147], v[204:207], v[4:7]
	v_mfma_f32_16x16x32_bf16 v[0:3], v[172:175], v[204:207], v[0:3]
	v_mfma_f32_16x16x32_bf16 v[44:47], v[148:151], v[184:187], v[44:47]
	v_mfma_f32_16x16x32_bf16 v[36:39], v[176:179], v[184:187], v[36:39]
	v_mfma_f32_16x16x32_bf16 v[28:31], v[148:151], v[192:195], v[28:31]
	v_mfma_f32_16x16x32_bf16 v[20:23], v[176:179], v[192:195], v[20:23]
	v_mfma_f32_16x16x32_bf16 v[12:15], v[148:151], v[200:203], v[12:15]
	v_mfma_f32_16x16x32_bf16 v[8:11], v[176:179], v[200:203], v[8:11]
	v_mfma_f32_16x16x32_bf16 v[4:7], v[148:151], v[212:215], v[4:7]
	v_mfma_f32_16x16x32_bf16 v[0:3], v[176:179], v[212:215], v[0:3]
	s_setprio 0
	s_add_u32 s8, s8, 0x1000
	s_addc_u32 s9, s9, 0
	s_add_u32 s41, s41, 0x100
	s_addc_u32 s46, s46, 0
	s_cmp_ge_i32 s55, s4
	s_mov_b32 s47, s55
	s_barrier
	s_cbranch_scc0 .LBB0_917
	s_and_b64 vcc, exec, s[36:37]
	s_cbranch_vccz .LBB0_922
	s_barrier
	s_cmp_lt_i32 s12, 0
	s_mov_b64 s[8:9], -1
	s_cbranch_scc1 .LBB0_923
